# strategy #7 DPP: retB quad sums (shfl_xor 1,2) as v_add_f32_dpp quad_perm instead of ds_bpermute round trips (8 sites), on top of the transpose-tile padding
# baseline (speedup 1.0000x reference)
.LBB0_586:
	v_add_u32_e32 v157, v161, v127
	v_sub_u32_e32 v158, v127, v89
	v_sub_u32_e32 v193, v127, v88
	v_sub_u32_e32 v204, v127, v91
	v_sub_u32_e32 v210, v127, v90
	v_sub_u32_e32 v211, v127, v93
	v_sub_u32_e32 v212, v127, v92
	v_sub_u32_e32 v213, v127, v95
	v_sub_u32_e32 v214, v127, v94
	v_cvt_f32_u32_e32 v39, v157
	v_cvt_f32_u32_e32 v40, v193
	v_cvt_f32_u32_e32 v41, v158
	v_cvt_f32_u32_e32 v42, v210
	v_cvt_f32_u32_e32 v43, v204
	v_cvt_f32_u32_e32 v44, v212
	v_cvt_f32_u32_e32 v45, v211
	v_cvt_f32_u32_e32 v46, v214
	v_cvt_f32_u32_e32 v47, v213
	ds_read_b128 v[32:35], v115
	ds_read_b128 v[172:175], v115 offset:32
	ds_read_b128 v[176:179], v115 offset:64
	ds_read_b128 v[180:183], v115 offset:96
	v_add_u32_e32 v36, 0xffffdc00, v156
	v_add_u32_e32 v37, 0xfffffc00, v156
	v_add_u32_e32 v38, 0xffffe000, v156
	ds_read_b64_tr_b16 v[188:189], v36
	ds_read_b64_tr_b16 v[190:191], v36 offset:512
	ds_read_b64_tr_b16 v[184:185], v37
	ds_read_b64_tr_b16 v[186:187], v37 offset:512
	s_waitcnt lgkmcnt(0)
	ds_read_b64_tr_b16 v[198:199], v38
	ds_read_b64_tr_b16 v[200:201], v38 offset:512
	ds_read_b64_tr_b16 v[194:195], v156
	ds_read_b64_tr_b16 v[196:197], v156 offset:512
	s_waitcnt lgkmcnt(0)
	v_mul_f32_e32 v223, v151, v39
	v_mul_f32_e32 v224, v151, v40
	v_mul_f32_e32 v225, v151, v41
	v_mul_f32_e32 v231, v151, v42
	v_mul_f32_e32 v232, v151, v43
	v_mul_f32_e32 v233, v151, v44
	v_mul_f32_e32 v234, v151, v45
	v_mul_f32_e32 v235, v151, v46
	v_mul_f32_e32 v236, v151, v47
	s_waitcnt lgkmcnt(3)
	v_mfma_f32_32x32x16_bf16 v[32:47], v[32:35], v[72:75], 0
	v_add_u32_e32 v221, -1, v157
	v_sub_u32_e32 v215, v127, v97
	v_sub_u32_e32 v216, v127, v96
	v_sub_u32_e32 v217, v127, v99
	v_sub_u32_e32 v218, v127, v98
	v_sub_u32_e32 v219, v127, v101
	v_sub_u32_e32 v220, v127, v100
	s_waitcnt lgkmcnt(2)
	v_mfma_f32_32x32x16_bf16 v[32:47], v[172:175], v[76:79], v[32:47]
	v_cvt_f32_u32_e32 v222, v221
	v_cvt_f32_u32_e32 v202, v216
	v_cvt_f32_u32_e32 v203, v215
	v_cvt_f32_u32_e32 v206, v218
	v_cvt_f32_u32_e32 v207, v217
	v_cvt_f32_u32_e32 v208, v220
	v_cvt_f32_u32_e32 v209, v219
	s_waitcnt lgkmcnt(1)
	v_mfma_f32_32x32x16_bf16 v[32:47], v[176:179], v[80:83], v[32:47]
	v_mul_f32_e32 v222, v151, v222
	v_mul_f32_e32 v237, v151, v202
	v_mul_f32_e32 v238, v151, v203
	v_mul_f32_e32 v239, v151, v206
	v_mul_f32_e32 v240, v151, v207
	v_mul_f32_e32 v208, v151, v208
	v_mul_f32_e32 v209, v151, v209
	s_waitcnt lgkmcnt(0)
	v_mfma_f32_32x32x16_bf16 v[32:47], v[180:183], v[84:87], v[32:47]
	v_exp_f32_e32 v223, v223
	v_exp_f32_e32 v202, v224
	v_exp_f32_e32 v203, v225
	v_exp_f32_e32 v172, v231
	v_exp_f32_e32 v173, v232
	v_exp_f32_e32 v174, v233
	v_exp_f32_e32 v175, v234
	v_exp_f32_e32 v222, v222
	v_exp_f32_e32 v206, v235
	v_exp_f32_e32 v207, v236
	v_exp_f32_e32 v176, v237
	v_exp_f32_e32 v177, v238
	v_exp_f32_e32 v178, v239
	v_exp_f32_e32 v179, v240
	v_exp_f32_e32 v208, v208
	v_exp_f32_e32 v209, v209
	v_mul_f32_e32 v180, v223, v32
	v_mul_f32_e32 v181, v222, v33
	v_cmp_lt_i32_e32 vcc, -1, v221
	v_pk_mul_f32 v[32:33], v[202:203], v[34:35]
	v_pk_mul_f32 v[34:35], v[172:173], v[36:37]
	v_pk_mul_f32 v[36:37], v[174:175], v[38:39]
	v_pk_mul_f32 v[38:39], v[206:207], v[40:41]
	v_pk_mul_f32 v[40:41], v[176:177], v[42:43]
	v_pk_mul_f32 v[42:43], v[178:179], v[44:45]
	v_pk_mul_f32 v[44:45], v[208:209], v[46:47]
	v_cmp_lt_i32_e64 s[0:1], -1, v157
	v_cndmask_b32_e32 v47, 0, v181, vcc
	v_cvt_pk_bf16_f32 v33, v32, v33
	v_cmp_lt_i32_e32 vcc, -1, v193
	v_cvt_pk_bf16_f32 v34, v34, v35
	v_cvt_pk_bf16_f32 v35, v36, v37
	v_cndmask_b32_e64 v46, 0, v180, s[0:1]
	v_cmp_lt_i32_e64 s[0:1], -1, v210
	v_cmp_lt_i32_e64 s[4:5], -1, v212
	v_cvt_pk_bf16_f32 v36, v38, v39
	v_cvt_pk_bf16_f32 v37, v40, v41
	v_cvt_pk_bf16_f32 v39, v44, v45
	v_lshrrev_b32_e32 v40, 16, v34
	v_cmp_lt_i32_e64 s[14:15], -1, v204
	v_lshrrev_b32_e32 v41, 16, v35
	v_cmp_lt_i32_e64 s[16:17], -1, v211
	v_cndmask_b32_e32 v45, 0, v33, vcc
	v_lshrrev_b32_e32 v33, 16, v33
	v_cmp_lt_i32_e32 vcc, -1, v158
	v_cndmask_b32_e64 v34, 0, v34, s[0:1]
	v_cndmask_b32_e64 v35, 0, v35, s[4:5]
	v_cndmask_b32_e32 v33, 0, v33, vcc
	v_cndmask_b32_e64 v40, 0, v40, s[14:15]
	v_cndmask_b32_e64 v41, 0, v41, s[16:17]
	v_cvt_pk_bf16_f32 v32, v46, v47
	v_perm_b32 v33, v33, v45, s29
	v_perm_b32 v34, v40, v34, s29
	v_perm_b32 v35, v41, v35, s29
	v_cmp_lt_i32_e64 s[6:7], -1, v214
	v_cvt_pk_bf16_f32 v38, v42, v43
	v_mfma_f32_32x32x16_bf16 v[0:15], v[188:191], v[32:35], v[0:15]
	v_cmp_lt_i32_e64 s[8:9], -1, v216
	v_cmp_lt_i32_e64 s[10:11], -1, v218
	v_cmp_lt_i32_e64 s[12:13], -1, v220
	v_lshrrev_b32_e32 v42, 16, v37
	v_cmp_lt_i32_e64 s[18:19], -1, v215
	v_lshrrev_b32_e32 v43, 16, v38
	v_cmp_lt_i32_e64 s[20:21], -1, v217
	v_mfma_f32_32x32x16_bf16 v[16:31], v[184:187], v[32:35], v[16:31]
	v_lshrrev_b32_e32 v44, 16, v39
	v_cmp_lt_i32_e64 s[22:23], -1, v219
	v_cndmask_b32_e64 v40, 0, v36, s[6:7]
	v_lshrrev_b32_e32 v36, 16, v36
	v_cmp_lt_i32_e32 vcc, -1, v213
	v_cndmask_b32_e64 v37, 0, v37, s[8:9]
	v_cndmask_b32_e64 v38, 0, v38, s[10:11]
	v_cndmask_b32_e64 v39, 0, v39, s[12:13]
	v_cndmask_b32_e32 v36, 0, v36, vcc
	v_cndmask_b32_e64 v33, 0, v42, s[18:19]
	v_cndmask_b32_e64 v34, 0, v43, s[20:21]
	v_cndmask_b32_e64 v35, 0, v44, s[22:23]
	v_perm_b32 v32, v36, v40, s29
	v_perm_b32 v33, v33, v37, s29
	v_perm_b32 v34, v34, v38, s29
	v_perm_b32 v35, v35, v39, s29
	s_add_i32 s33, s33, -1
	v_subrev_u32_e32 v127, 32, v127
	v_mfma_f32_32x32x16_bf16 v[0:15], v[198:201], v[32:35], v[0:15]
	v_add_u32_e32 v115, 0x1200, v115
	s_cmp_lg_u32 s33, 0
	v_add_u32_e32 v156, 0x800, v156
	v_mfma_f32_32x32x16_bf16 v[16:31], v[194:197], v[32:35], v[16:31]
	s_cbranch_scc1 .LBB0_586
	v_or_b32_e32 v32, s41, v228
	s_movk_i32 s0, 0x284
	v_mul_lo_u32 v32, v32, s0
	s_mul_i32 s0, s3, 0x140
	s_add_i32 s0, s0, 0
	v_add_u32_e32 v32, s0, v32
	v_add_u32_e32 v172, v32, v126
	s_waitcnt lgkmcnt(0)
	s_barrier
	ds_write2_b32 v172, v0, v1 offset1:1
	ds_write2_b32 v172, v2, v3 offset0:2 offset1:3
	ds_write2_b32 v172, v4, v5 offset0:8 offset1:9
	ds_write2_b32 v172, v6, v7 offset0:10 offset1:11
	ds_write2_b32 v172, v8, v9 offset0:16 offset1:17
	ds_write2_b32 v172, v10, v11 offset0:18 offset1:19
	ds_write2_b32 v172, v12, v13 offset0:24 offset1:25
	ds_write2_b32 v172, v14, v15 offset0:26 offset1:27
	ds_write2_b32 v172, v16, v17 offset0:40 offset1:41
	ds_write2_b32 v172, v18, v19 offset0:42 offset1:43
	ds_write2_b32 v172, v20, v21 offset0:48 offset1:49
	ds_write2_b32 v172, v22, v23 offset0:50 offset1:51
	ds_write2_b32 v172, v24, v25 offset0:56 offset1:57
	ds_write2_b32 v172, v26, v27 offset0:58 offset1:59
	ds_write2_b32 v172, v28, v29 offset0:64 offset1:65
	ds_write2_b32 v172, v30, v31 offset0:66 offset1:67
	v_mul_u32_u24_e32 v0, 0x284, v112
	v_lshlrev_b32_e32 v32, 2, v121
	v_mad_u32_u24 v158, v121, 5, v0
	v_mbcnt_lo_u32_b32 v0, -1, 0
	v_mbcnt_hi_u32_b32 v182, -1, v0
	v_and_b32_e32 v1, 64, v182
	v_xor_b32_e32 v0, 1, v182
	v_add_u32_e32 v183, 64, v1
	v_cmp_lt_i32_e32 vcc, v0, v183
	s_lshl_b32 s0, s36, 2
	s_add_u32 s0, s72, s0
	v_cndmask_b32_e32 v0, v182, v0, vcc
	v_lshlrev_b32_e32 v157, 2, v0
	v_xor_b32_e32 v0, 2, v182
	v_cmp_lt_i32_e32 vcc, v0, v183
	s_waitcnt lgkmcnt(0)
	s_barrier
	s_addc_u32 s1, s73, 0
	v_cndmask_b32_e32 v0, v182, v0, vcc
	v_mov_b32_e32 v33, 0
	v_readlane_b32 s4, v254, 0
	v_lshlrev_b32_e32 v156, 2, v0
	v_lshl_add_u64 v[80:81], s[0:1], 0, v[32:33]
	global_load_dwordx4 v[16:19], v32, s[0:1] offset:48
	global_load_dwordx4 v[20:23], v32, s[0:1] offset:32
	global_load_dwordx4 v[24:27], v32, s[0:1] offset:16
	global_load_dwordx4 v[28:31], v32, s[0:1]
	global_load_dwordx4 v[0:3], v32, s[0:1] offset:112
	global_load_dwordx4 v[4:7], v32, s[0:1] offset:96
	global_load_dwordx4 v[8:11], v32, s[0:1] offset:80
	global_load_dwordx4 v[12:15], v32, s[0:1] offset:64
	s_lshl_b64 s[0:1], s[34:35], 12
	v_readlane_b32 s6, v254, 2
	v_readlane_b32 s7, v254, 3
	s_add_u32 s0, s6, s0
	v_lshlrev_b32_e32 v32, 11, v119
	s_addc_u32 s1, s7, s1
	v_and_b32_e32 v32, 0x7f800, v32
	v_lshl_add_u64 v[34:35], s[0:1], 0, v[32:33]
	v_lshlrev_b32_e32 v32, 16, v70
	v_and_b32_e32 v38, 0xffff0000, v70
	v_mul_f32_e32 v36, 0xbfb8aa3b, v32
	v_mul_f32_e32 v37, 0xbfb8aa3b, v38
	v_exp_f32_e32 v36, v36
	v_exp_f32_e32 v37, v37
	v_lshlrev_b32_e32 v45, 16, v69
	v_and_b32_e32 v46, 0xffff0000, v69
	v_lshlrev_b32_e32 v74, 16, v71
	v_pk_add_f32 v[36:37], v[36:37], 1.0 op_sel_hi:[1,0]
	v_and_b32_e32 v44, 0xffff0000, v71
	v_lshlrev_b32_e32 v79, 16, v66
	v_and_b32_e32 v66, 0xffff0000, v66
	v_lshlrev_b32_e32 v119, 16, v67
	v_rcp_f32_e32 v39, v37
	s_nop 0
	v_mul_f32_e32 v37, v38, v39
	v_mul_f32_e32 v39, 0xbfb8aa3b, v46
	v_mul_f32_e32 v38, 0xbfb8aa3b, v45
	v_exp_f32_e32 v38, v38
	v_exp_f32_e32 v39, v39
	s_nop 0
	v_pk_add_f32 v[38:39], v[38:39], 1.0 op_sel_hi:[1,0]
	v_rcp_f32_e32 v40, v36
	s_nop 0
	v_mul_f32_e32 v36, v32, v40
	v_and_b32_e32 v86, 0xffff0000, v67
	v_rcp_f32_e32 v32, v39
	s_nop 0
	v_mul_f32_e32 v39, v46, v32
	v_lshlrev_b32_e32 v87, 16, v65
	v_lshlrev_b32_e32 v42, 16, v68
	v_and_b32_e32 v43, 0xffff0000, v68
	v_mul_f32_e32 v40, 0xbfb8aa3b, v42
	v_mul_f32_e32 v41, 0xbfb8aa3b, v43
	v_exp_f32_e32 v40, v40
	v_exp_f32_e32 v41, v41
	v_rcp_f32_e32 v32, v38
	s_nop 0
	v_mul_f32_e32 v38, v45, v32
	v_and_b32_e32 v65, 0xffff0000, v65
	v_lshlrev_b32_e32 v121, 16, v64
	v_pk_add_f32 v[40:41], v[40:41], 1.0 op_sel_hi:[1,0]
	v_and_b32_e32 v126, 0xffff0000, v64
	v_mul_f32_e32 v64, 0xbfb8aa3b, v121
	v_lshlrev_b32_e32 v174, 16, v62
	v_and_b32_e32 v62, 0xffff0000, v62
	v_rcp_f32_e32 v45, v41
	s_nop 0
	v_mul_f32_e32 v41, v43, v45
	v_lshlrev_b32_e32 v184, 16, v60
	v_rcp_f32_e32 v43, v40
	s_nop 0
	v_mul_f32_e32 v40, v42, v43
	v_mul_f32_e32 v42, 0xbfb8aa3b, v74
	v_mul_f32_e32 v43, 0xbfb8aa3b, v44
	v_exp_f32_e32 v42, v42
	v_exp_f32_e32 v43, v43
	ds_read2_b32 v[46:47], v158 offset0:6 offset1:7
	ds_read2_b32 v[68:69], v158 offset0:4 offset1:5
	ds_read2_b32 v[70:71], v158 offset0:2 offset1:3
	ds_read2_b32 v[72:73], v158 offset1:1
	v_readlane_b32 s5, v254, 1
	s_mov_b32 s37, 0
	v_pk_add_f32 v[42:43], v[42:43], 1.0 op_sel_hi:[1,0]
	s_lshl_b32 s36, s36, 1
	s_waitcnt lgkmcnt(0)
	v_add_f32_e32 v32, 0, v72
	v_add_f32_e32 v32, v32, v73
	v_add_f32_e32 v32, v32, v70
	v_rcp_f32_e32 v45, v43
	s_nop 0
	v_mul_f32_e32 v43, v44, v45
	v_mul_f32_e32 v44, 0xbfb8aa3b, v79
	v_mul_f32_e32 v45, 0xbfb8aa3b, v66
	v_exp_f32_e32 v44, v44
	v_exp_f32_e32 v45, v45
	v_rcp_f32_e32 v75, v42
	s_nop 0
	v_mul_f32_e32 v42, v74, v75
	v_pk_add_f32 v[44:45], v[44:45], 1.0 op_sel_hi:[1,0]
	v_add_f32_e32 v32, v32, v71
	v_add_f32_e32 v32, v32, v68
	v_add_f32_e32 v32, v32, v69
	v_add_f32_e32 v32, v32, v46
	v_rcp_f32_e32 v67, v45
	s_nop 0
	v_mul_f32_e32 v45, v66, v67
	v_mul_f32_e32 v67, 0xbfb8aa3b, v65
	v_mul_f32_e32 v66, 0xbfb8aa3b, v87
	v_exp_f32_e32 v66, v66
	v_exp_f32_e32 v67, v67
	s_nop 0
	v_pk_add_f32 v[66:67], v[66:67], 1.0 op_sel_hi:[1,0]
	v_rcp_f32_e32 v74, v44
	s_nop 0
	v_mul_f32_e32 v44, v79, v74
	v_add_f32_e32 v32, v32, v47
	v_rcp_f32_e32 v74, v67
	s_nop 0
	v_mul_f32_e32 v65, v65, v74
	v_lshl_add_u64 v[34:35], v[34:35], 0, s[36:37]
	v_exp_f32_e32 v74, v64
	v_mul_f32_e32 v64, 0xbfb8aa3b, v126
	v_exp_f32_e32 v75, v64
	v_rcp_f32_e32 v64, v66
	s_nop 0
	v_mul_f32_e32 v64, v87, v64
	ds_read2_b32 v[76:77], v158 offset0:14 offset1:15
	ds_read2_b32 v[78:79], v158 offset0:12 offset1:13
	ds_read2_b32 v[82:83], v158 offset0:10 offset1:11
	ds_read2_b32 v[84:85], v158 offset0:8 offset1:9
	v_mov_b32_e32 v115, v33
	v_pk_add_f32 v[74:75], v[74:75], 1.0 op_sel_hi:[1,0]
	v_lshl_add_u64 v[34:35], v[34:35], 0, v[114:115]
	s_waitcnt lgkmcnt(0)
	v_add_f32_e32 v32, v32, v84
	v_add_f32_e32 v32, v32, v85
	v_add_f32_e32 v32, v32, v82
	v_rcp_f32_e32 v67, v75
	s_nop 0
	v_mul_f32_e32 v67, v126, v67
	v_add_f32_e32 v32, v32, v83
	v_rcp_f32_e32 v66, v74
	s_nop 0
	v_mul_f32_e32 v66, v121, v66
	v_mul_f32_e32 v74, 0xbfb8aa3b, v119
	v_mul_f32_e32 v75, 0xbfb8aa3b, v86
	v_exp_f32_e32 v74, v74
	v_exp_f32_e32 v75, v75
	v_add_f32_e32 v32, v32, v78
	v_add_f32_e32 v32, v32, v79
	v_add_f32_e32 v32, v32, v76
	v_pk_add_f32 v[74:75], v[74:75], 1.0 op_sel_hi:[1,0]
	v_add_f32_e32 v32, v32, v77
	s_bitset1_b32 s34, 7
	s_movk_i32 s3, 0x1800
	v_rcp_f32_e32 v87, v75
	s_nop 0
	v_mul_f32_e32 v75, v86, v87
	v_mul_f32_e32 v86, 0xbfb8aa3b, v174
	v_mul_f32_e32 v87, 0xbfb8aa3b, v62
	v_exp_f32_e32 v86, v86
	v_exp_f32_e32 v87, v87
	v_rcp_f32_e32 v121, v74
	s_nop 0
	v_mul_f32_e32 v74, v119, v121
	v_pk_add_f32 v[86:87], v[86:87], 1.0 op_sel_hi:[1,0]
	v_lshlrev_b32_e32 v119, 16, v63
	v_and_b32_e32 v121, 0xffff0000, v63
	v_lshlrev_b32_e32 v173, 16, v61
	v_and_b32_e32 v61, 0xffff0000, v61
	v_mul_f32_e32 v126, 0xbfb8aa3b, v173
	v_mul_f32_e32 v127, 0xbfb8aa3b, v61
	v_rcp_f32_e32 v63, v87
	s_nop 0
	v_mul_f32_e32 v63, v62, v63
	v_exp_f32_e32 v126, v126
	v_exp_f32_e32 v127, v127
	s_nop 0
	v_pk_add_f32 v[126:127], v[126:127], 1.0 op_sel_hi:[1,0]
	v_rcp_f32_e32 v62, v86
	s_nop 0
	v_mul_f32_e32 v62, v174, v62
	v_rcp_f32_e32 v87, v127
	s_nop 0
	v_mul_f32_e32 v87, v61, v87
	v_and_b32_e32 v127, 0xffff0000, v60
	v_mul_f32_e32 v60, 0xbfb8aa3b, v184
	v_mul_f32_e32 v61, 0xbfb8aa3b, v127
	v_exp_f32_e32 v60, v60
	v_exp_f32_e32 v61, v61
	v_rcp_f32_e32 v86, v126
	s_nop 0
	v_mul_f32_e32 v86, v173, v86
	ds_read2_b32 v[174:175], v158 offset0:22 offset1:23
	ds_read2_b32 v[176:177], v158 offset0:20 offset1:21
	ds_read2_b32 v[178:179], v158 offset0:18 offset1:19
	ds_read2_b32 v[180:181], v158 offset0:16 offset1:17
	v_pk_add_f32 v[60:61], v[60:61], 1.0 op_sel_hi:[1,0]
	s_nop 0
	s_waitcnt lgkmcnt(0)
	v_add_f32_e32 v32, v32, v180
	v_add_f32_e32 v32, v32, v181
	v_add_f32_e32 v32, v32, v178
	v_rcp_f32_e32 v126, v61
	s_nop 0
	v_mul_f32_e32 v127, v127, v126
	v_add_f32_e32 v32, v32, v179
	v_rcp_f32_e32 v126, v60
	s_nop 0
	v_mul_f32_e32 v126, v184, v126
	v_mul_f32_e32 v60, 0xbfb8aa3b, v119
	v_mul_f32_e32 v61, 0xbfb8aa3b, v121
	v_exp_f32_e32 v60, v60
	v_exp_f32_e32 v61, v61
	v_add_f32_e32 v32, v32, v176
	v_add_f32_e32 v32, v32, v177
	v_add_f32_e32 v32, v32, v174
	v_pk_add_f32 v[184:185], v[60:61], 1.0 op_sel_hi:[1,0]
	ds_read2_b32 v[186:187], v158 offset0:30 offset1:31
	ds_read2_b32 v[60:61], v158 offset0:28 offset1:29
	ds_read2_b32 v[188:189], v158 offset0:26 offset1:27
	ds_read2_b32 v[190:191], v158 offset0:24 offset1:25
	v_add_f32_e32 v32, v32, v175
	s_waitcnt lgkmcnt(0)
	v_add_f32_e32 v32, v32, v190
	v_add_f32_e32 v32, v32, v191
	v_add_f32_e32 v32, v32, v188
	v_add_f32_e32 v32, v32, v189
	v_add_f32_e32 v32, v32, v60
	v_add_f32_e32 v32, v32, v61
	v_add_f32_e32 v32, v32, v186
	v_add_f32_e32 v32, v32, v187
	s_nop 1
	v_add_f32_dpp v32, v32, v32 quad_perm:[1,0,3,2] row_mask:0xf bank_mask:0xf
	s_waitcnt lgkmcnt(0)
	s_nop 1
	v_add_f32_dpp v32, v32, v32 quad_perm:[2,3,0,1] row_mask:0xf bank_mask:0xf
	v_rcp_f32_e32 v173, v185
	s_nop 0
	v_mul_f32_e32 v185, v121, v173
	s_waitcnt lgkmcnt(0)
	v_mul_f32_e32 v32, 0x3c000000, v32
	v_pk_add_f32 v[72:73], v[72:73], v[32:33] op_sel_hi:[1,0] neg_lo:[0,1] neg_hi:[0,1]
	v_pk_add_f32 v[70:71], v[70:71], v[32:33] op_sel_hi:[1,0] neg_lo:[0,1] neg_hi:[0,1]
	v_pk_mul_f32 v[194:195], v[72:73], v[72:73]
	v_pk_mul_f32 v[196:197], v[70:71], v[70:71]
	v_pk_add_f32 v[198:199], v[68:69], v[32:33] op_sel_hi:[1,0] neg_lo:[0,1] neg_hi:[0,1]
	v_pk_add_f32 v[202:203], v[46:47], v[32:33] op_sel_hi:[1,0] neg_lo:[0,1] neg_hi:[0,1]
	v_pk_add_f32 v[84:85], v[84:85], v[32:33] op_sel_hi:[1,0] neg_lo:[0,1] neg_hi:[0,1]
	v_pk_add_f32 v[82:83], v[82:83], v[32:33] op_sel_hi:[1,0] neg_lo:[0,1] neg_hi:[0,1]
	v_pk_add_f32 v[78:79], v[78:79], v[32:33] op_sel_hi:[1,0] neg_lo:[0,1] neg_hi:[0,1]
	v_pk_add_f32 v[76:77], v[76:77], v[32:33] op_sel_hi:[1,0] neg_lo:[0,1] neg_hi:[0,1]
	v_pk_add_f32 v[180:181], v[180:181], v[32:33] op_sel_hi:[1,0] neg_lo:[0,1] neg_hi:[0,1]
	v_pk_add_f32 v[178:179], v[178:179], v[32:33] op_sel_hi:[1,0] neg_lo:[0,1] neg_hi:[0,1]
	v_pk_add_f32 v[176:177], v[176:177], v[32:33] op_sel_hi:[1,0] neg_lo:[0,1] neg_hi:[0,1]
	v_pk_add_f32 v[174:175], v[174:175], v[32:33] op_sel_hi:[1,0] neg_lo:[0,1] neg_hi:[0,1]
	v_pk_add_f32 v[190:191], v[190:191], v[32:33] op_sel_hi:[1,0] neg_lo:[0,1] neg_hi:[0,1]
	v_pk_add_f32 v[68:69], v[188:189], v[32:33] op_sel_hi:[1,0] neg_lo:[0,1] neg_hi:[0,1]
	v_pk_add_f32 v[60:61], v[60:61], v[32:33] op_sel_hi:[1,0] neg_lo:[0,1] neg_hi:[0,1]
	v_pk_add_f32 v[46:47], v[186:187], v[32:33] op_sel_hi:[1,0] neg_lo:[0,1] neg_hi:[0,1]
	v_add_f32_e32 v32, v194, v195
	v_add_f32_e32 v32, v196, v32
	v_pk_mul_f32 v[200:201], v[198:199], v[198:199]
	v_add_f32_e32 v32, v197, v32
	v_add_f32_e32 v32, v200, v32
	v_pk_mul_f32 v[206:207], v[202:203], v[202:203]
	v_add_f32_e32 v32, v201, v32
	v_add_f32_e32 v32, v206, v32
	v_pk_mul_f32 v[208:209], v[84:85], v[84:85]
	v_add_f32_e32 v32, v207, v32
	v_add_f32_e32 v32, v208, v32
	v_pk_mul_f32 v[210:211], v[82:83], v[82:83]
	v_add_f32_e32 v32, v209, v32
	v_add_f32_e32 v32, v210, v32
	v_pk_mul_f32 v[212:213], v[78:79], v[78:79]
	v_add_f32_e32 v32, v211, v32
	v_add_f32_e32 v32, v212, v32
	v_pk_mul_f32 v[214:215], v[76:77], v[76:77]
	v_add_f32_e32 v32, v213, v32
	v_add_f32_e32 v32, v214, v32
	v_pk_mul_f32 v[216:217], v[180:181], v[180:181]
	v_add_f32_e32 v32, v215, v32
	v_add_f32_e32 v32, v216, v32
	v_pk_mul_f32 v[218:219], v[178:179], v[178:179]
	v_add_f32_e32 v32, v217, v32
	v_add_f32_e32 v32, v218, v32
	v_pk_mul_f32 v[220:221], v[176:177], v[176:177]
	v_add_f32_e32 v32, v219, v32
	v_add_f32_e32 v32, v220, v32
	v_pk_mul_f32 v[222:223], v[174:175], v[174:175]
	v_add_f32_e32 v32, v221, v32
	v_add_f32_e32 v32, v222, v32
	v_pk_mul_f32 v[224:225], v[190:191], v[190:191]
	v_add_f32_e32 v32, v223, v32
	v_add_f32_e32 v32, v224, v32
	v_pk_mul_f32 v[188:189], v[68:69], v[68:69]
	v_add_f32_e32 v32, v225, v32
	v_add_f32_e32 v32, v188, v32
	v_pk_mul_f32 v[232:233], v[60:61], v[60:61]
	v_add_f32_e32 v32, v189, v32
	v_add_f32_e32 v32, v232, v32
	v_pk_mul_f32 v[186:187], v[46:47], v[46:47]
	v_add_f32_e32 v32, v233, v32
	v_add_f32_e32 v32, v186, v32
	v_add_f32_e32 v32, v187, v32
	s_nop 1
	v_add_f32_dpp v32, v32, v32 quad_perm:[1,0,3,2] row_mask:0xf bank_mask:0xf
	s_mov_b32 s0, 0xf800000
	s_waitcnt lgkmcnt(0)
	s_nop 1
	v_add_f32_dpp v32, v32, v32 quad_perm:[2,3,0,1] row_mask:0xf bank_mask:0xf
	s_waitcnt lgkmcnt(0)
	v_mov_b32_e32 v173, 0x358637bd
	v_fmac_f32_e32 v173, 0x3c000000, v32
	v_mul_f32_e32 v32, 0x4f800000, v173
	v_cmp_gt_f32_e64 s[0:1], s0, v173
	s_nop 1
	v_cndmask_b32_e64 v32, v173, v32, s[0:1]
	v_sqrt_f32_e32 v173, v32
	s_nop 0
	v_add_u32_e32 v187, -1, v173
	v_fma_f32 v188, -v187, v173, v32
	v_cmp_ge_f32_e64 s[4:5], 0, v188
	v_add_u32_e32 v188, 1, v173
	v_rcp_f32_e32 v121, v184
	s_nop 0
	v_mul_f32_e32 v184, v119, v121
	v_cndmask_b32_e64 v187, v173, v187, s[4:5]
	v_fma_f32 v173, -v188, v173, v32
	v_cmp_lt_f32_e64 s[4:5], 0, v173
	s_nop 1
	v_cndmask_b32_e64 v173, v187, v188, s[4:5]
	v_mul_f32_e32 v187, 0x37800000, v173
	v_cndmask_b32_e64 v173, v173, v187, s[0:1]
	v_mov_b32_e32 v187, 0x260
	v_cmp_class_f32_e64 s[0:1], v32, v187
	s_nop 1
	v_cndmask_b32_e64 v32, v173, v32, s[0:1]
	v_rcp_f32_e32 v32, v32
	s_nop 0
	v_pk_mul_f32 v[72:73], v[72:73], v[32:33] op_sel_hi:[1,0]
	v_mov_b32_e32 v119, v33
	s_waitcnt vmcnt(4)
	v_pk_mul_f32 v[28:29], v[28:29], v[72:73]
	v_mov_b32_e32 v121, v33
	v_pk_mul_f32 v[28:29], v[40:41], v[28:29]
	v_pk_mul_f32 v[40:41], v[70:71], v[32:33] op_sel_hi:[1,0]
	s_nop 0
	v_pk_mul_f32 v[30:31], v[30:31], v[40:41]
	v_lshlrev_b32_e32 v40, 16, v50
	v_pk_mul_f32 v[30:31], v[38:39], v[30:31]
	v_pk_mul_f32 v[38:39], v[198:199], v[32:33] op_sel_hi:[1,0]
	v_and_b32_e32 v41, 0xffff0000, v50
	v_pk_mul_f32 v[24:25], v[24:25], v[38:39]
	v_pk_fma_f32 v[40:41], v[124:125], v[146:147], v[40:41] op_sel_hi:[0,1,1]
	v_pk_mul_f32 v[36:37], v[36:37], v[24:25]
	v_pk_mul_f32 v[24:25], v[202:203], v[32:33] op_sel_hi:[1,0]
	s_nop 0
	v_pk_mul_f32 v[24:25], v[26:27], v[24:25]
	v_cvt_pk_bf16_f32 v26, v36, v37
	v_pk_mul_f32 v[38:39], v[42:43], v[24:25]
	v_cvt_pk_bf16_f32 v24, v28, v29
	v_cvt_pk_bf16_f32 v25, v30, v31
	v_cvt_pk_bf16_f32 v27, v38, v39
	global_store_dwordx4 v[34:35], v[24:27], off
	v_mov_b32_e32 v28, 0x1800
	v_and_b32_e32 v29, 0xffff0000, v52
	v_pk_mul_f32 v[24:25], v[84:85], v[32:33] op_sel_hi:[1,0]
	v_lshlrev_b32_e32 v30, 16, v53
	v_pk_mul_f32 v[20:21], v[20:21], v[24:25]
	v_pk_mul_f32 v[24:25], v[82:83], v[32:33] op_sel_hi:[1,0]
	v_pk_mul_f32 v[20:21], v[66:67], v[20:21]
	v_pk_mul_f32 v[22:23], v[22:23], v[24:25]
	v_pk_mul_f32 v[24:25], v[78:79], v[32:33] op_sel_hi:[1,0]
	v_pk_mul_f32 v[22:23], v[64:65], v[22:23]
	v_pk_mul_f32 v[16:17], v[16:17], v[24:25]
	v_lshl_add_u64 v[82:83], s[34:35], 0, v[112:113]
	v_pk_mul_f32 v[24:25], v[44:45], v[16:17]
	v_pk_mul_f32 v[16:17], v[76:77], v[32:33] op_sel_hi:[1,0]
	v_and_b32_e32 v31, 0xffff0000, v53
	v_pk_mul_f32 v[16:17], v[18:19], v[16:17]
	v_cvt_pk_bf16_f32 v18, v24, v25
	v_pk_mul_f32 v[26:27], v[74:75], v[16:17]
	v_cvt_pk_bf16_f32 v16, v20, v21
	v_cvt_pk_bf16_f32 v17, v22, v23
	v_cvt_pk_bf16_f32 v19, v26, v27
	global_store_dwordx4 v[34:35], v[16:19], off offset:16
	v_lshlrev_b32_e32 v20, 16, v56
	v_and_b32_e32 v21, 0xffff0000, v56
	v_pk_mul_f32 v[16:17], v[180:181], v[32:33] op_sel_hi:[1,0]
	v_mov_b64_e32 v[24:25], s[26:27]
	s_waitcnt vmcnt(2)
	v_pk_mul_f32 v[12:13], v[12:13], v[16:17]
	v_pk_mul_f32 v[16:17], v[178:179], v[32:33] op_sel_hi:[1,0]
	v_pk_mul_f32 v[12:13], v[126:127], v[12:13]
	v_pk_mul_f32 v[14:15], v[14:15], v[16:17]
	v_pk_mul_f32 v[16:17], v[176:177], v[32:33] op_sel_hi:[1,0]
	v_pk_mul_f32 v[14:15], v[86:87], v[14:15]
	v_pk_mul_f32 v[8:9], v[8:9], v[16:17]
	v_lshlrev_b32_e32 v36, 16, v48
	v_pk_mul_f32 v[16:17], v[62:63], v[8:9]
	v_pk_mul_f32 v[8:9], v[174:175], v[32:33] op_sel_hi:[1,0]
	v_and_b32_e32 v37, 0xffff0000, v48
	v_pk_mul_f32 v[8:9], v[10:11], v[8:9]
	v_mul_f32_e32 v10, 0xbfb8aa3b, v20
	v_mul_f32_e32 v11, 0xbfb8aa3b, v21
	v_exp_f32_e32 v10, v10
	v_exp_f32_e32 v11, v11
	v_pk_mul_f32 v[18:19], v[184:185], v[8:9]
	v_cvt_pk_bf16_f32 v8, v12, v13
	v_cvt_pk_bf16_f32 v9, v14, v15
	v_pk_add_f32 v[12:13], v[10:11], 1.0 op_sel_hi:[1,0]
	v_cvt_pk_bf16_f32 v10, v16, v17
	v_cvt_pk_bf16_f32 v11, v18, v19
	global_store_dwordx4 v[34:35], v[8:11], off offset:32
	v_and_b32_e32 v16, 0xffff0000, v57
	v_lshlrev_b32_e32 v38, 16, v49
	v_rcp_f32_e32 v9, v13
	s_nop 0
	v_mul_f32_e32 v9, v21, v9
	v_lshlrev_b32_e32 v15, 16, v57
	v_mul_f32_e32 v10, 0xbfb8aa3b, v15
	v_mul_f32_e32 v11, 0xbfb8aa3b, v16
	v_exp_f32_e32 v10, v10
	v_exp_f32_e32 v11, v11
	v_rcp_f32_e32 v8, v12
	s_nop 0
	v_mul_f32_e32 v8, v20, v8
	v_pk_mul_f32 v[12:13], v[190:191], v[32:33] op_sel_hi:[1,0]
	v_pk_add_f32 v[10:11], v[10:11], 1.0 op_sel_hi:[1,0]
	v_pk_mul_f32 v[4:5], v[4:5], v[12:13]
	v_pk_mul_f32 v[4:5], v[8:9], v[4:5]
	v_lshl_add_u64 v[20:21], s[34:35], 0, v[116:117]
	v_mad_u64_u32 v[22:23], s[4:5], v20, s3, v[24:25]
	v_rcp_f32_e32 v9, v11
	s_nop 0
	v_mul_f32_e32 v9, v16, v9
	v_lshlrev_b32_e32 v16, 16, v58
	v_and_b32_e32 v17, 0xffff0000, v58
	v_mul_f32_e32 v12, 0xbfb8aa3b, v16
	v_mul_f32_e32 v13, 0xbfb8aa3b, v17
	v_exp_f32_e32 v12, v12
	v_exp_f32_e32 v13, v13
	v_rcp_f32_e32 v8, v10
	s_nop 0
	v_mul_f32_e32 v8, v15, v8
	v_mad_u32_u24 v23, v21, s3, v23
	v_pk_add_f32 v[10:11], v[12:13], 1.0 op_sel_hi:[1,0]
	v_pk_mul_f32 v[12:13], v[68:69], v[32:33] op_sel_hi:[1,0]
	v_pk_mul_f32 v[6:7], v[6:7], v[12:13]
	v_and_b32_e32 v39, 0xffff0000, v49
	v_pk_mul_f32 v[6:7], v[8:9], v[6:7]
	v_rcp_f32_e32 v9, v11
	s_nop 0
	v_mul_f32_e32 v9, v17, v9
	v_lshlrev_b32_e32 v15, 16, v59
	v_and_b32_e32 v17, 0xffff0000, v59
	v_mul_f32_e32 v12, 0xbfb8aa3b, v15
	v_mul_f32_e32 v13, 0xbfb8aa3b, v17
	v_exp_f32_e32 v12, v12
	v_exp_f32_e32 v13, v13
	v_rcp_f32_e32 v8, v10
	s_nop 0
	v_mul_f32_e32 v8, v16, v8
	v_pk_fma_f32 v[30:31], v[124:125], v[136:137], v[30:31] op_sel_hi:[0,1,1]
	v_pk_add_f32 v[10:11], v[12:13], 1.0 op_sel_hi:[1,0]
	v_pk_mul_f32 v[12:13], v[60:61], v[32:33] op_sel_hi:[1,0]
	v_pk_mul_f32 v[0:1], v[0:1], v[12:13]
	v_pk_fma_f32 v[36:37], v[124:125], v[142:143], v[36:37] op_sel_hi:[0,1,1]
	v_pk_mul_f32 v[8:9], v[8:9], v[0:1]
	v_rcp_f32_e32 v1, v11
	s_nop 0
	v_mul_f32_e32 v1, v17, v1
	v_rcp_f32_e32 v0, v10
	s_nop 0
	v_mul_f32_e32 v0, v15, v0
	v_pk_mul_f32 v[10:11], v[46:47], v[32:33] op_sel_hi:[1,0]
	v_or_b32_e32 v16, s34, v205
	v_pk_mul_f32 v[2:3], v[2:3], v[10:11]
	v_mad_u64_u32 v[16:17], s[0:1], v16, s3, v[24:25]
	v_pk_mul_f32 v[10:11], v[0:1], v[2:3]
	v_cvt_pk_bf16_f32 v0, v4, v5
	v_cvt_pk_bf16_f32 v1, v6, v7
	v_cvt_pk_bf16_f32 v2, v8, v9
	v_cvt_pk_bf16_f32 v3, v10, v11
	global_store_dwordx4 v[34:35], v[0:3], off offset:48
	v_or_b32_e32 v8, s34, v154
	v_lshl_add_u64 v[10:11], s[34:35], 0, v[122:123]
	v_or_b32_e32 v0, s34, v152
	v_or_b32_e32 v2, s34, v153
	v_mad_u64_u32 v[0:1], s[0:1], v0, s3, v[24:25]
	v_mad_u64_u32 v[2:3], s[0:1], v2, s3, v[24:25]
	v_mad_u64_u32 v[8:9], s[0:1], v8, s3, v[24:25]
	v_mad_u64_u32 v[12:13], s[0:1], v10, s3, v[24:25]
	v_mad_u32_u24 v1, s35, v28, v1
	v_mad_u32_u24 v3, s35, v28, v3
	v_mad_u32_u24 v9, s35, v28, v9
	v_mad_u32_u24 v13, v11, s3, v13
	v_lshl_add_u64 v[0:1], v[0:1], 0, s[36:37]
	v_lshl_add_u64 v[2:3], v[2:3], 0, s[36:37]
	v_lshl_add_u64 v[8:9], v[8:9], 0, s[36:37]
	v_lshl_add_u64 v[10:11], v[12:13], 0, s[36:37]
	v_mad_u32_u24 v17, s35, v28, v17
	s_lshl_b32 s0, s31, 1
	s_mov_b32 s1, s37
	s_waitcnt lgkmcnt(0)
	s_barrier
	v_lshl_add_u64 v[0:1], v[0:1], 0, v[118:119]
	v_lshl_add_u64 v[4:5], v[2:3], 0, v[118:119]
	v_lshl_add_u64 v[8:9], v[8:9], 0, v[118:119]
	v_lshl_add_u64 v[12:13], v[10:11], 0, v[118:119]
	v_lshl_add_u64 v[16:17], v[16:17], 0, s[0:1]
	v_lshl_add_u64 v[20:21], v[22:23], 0, s[0:1]
	global_load_dwordx4 v[0:3], v[0:1], off offset:1024
	s_nop 0
	global_load_dwordx4 v[4:7], v[4:5], off offset:1024
	s_nop 0
	global_load_dwordx4 v[8:11], v[8:9], off offset:1024
	s_nop 0
	global_load_dwordx4 v[12:15], v[12:13], off offset:1024
	v_lshl_add_u64 v[16:17], v[16:17], 0, v[120:121]
	v_lshl_add_u64 v[20:21], v[20:21], 0, v[120:121]
	global_load_dwordx4 v[16:19], v[16:17], off offset:512
	s_add_u32 s4, s34, s41
	global_load_dwordx4 v[20:23], v[20:21], off offset:512
	v_or_b32_e32 v26, s4, v228
	s_addc_u32 s6, s35, 0
	v_mad_u64_u32 v[26:27], s[4:5], v26, s3, v[24:25]
	v_mad_u32_u24 v27, s6, v28, v27
	v_lshl_add_u64 v[26:27], v[26:27], 0, s[0:1]
	v_lshlrev_b32_e32 v32, 1, v155
	v_lshl_add_u64 v[26:27], v[26:27], 0, v[32:33]
	global_load_dwordx4 v[64:67], v[26:27], off
	global_load_dwordx4 v[68:71], v[26:27], off offset:32
	global_load_dwordx4 v[72:75], v[26:27], off offset:64
	global_load_dwordx4 v[76:79], v[26:27], off offset:96
	v_mad_u64_u32 v[24:25], s[0:1], v82, s3, v[24:25]
	v_mad_u32_u24 v25, v83, s3, v25
	v_lshl_add_u64 v[24:25], v[24:25], 0, s[36:37]
	v_lshl_add_u64 v[24:25], v[24:25], 0, v[114:115]
	v_lshlrev_b32_e32 v28, 16, v52
	v_lshlrev_b32_e32 v32, 16, v54
	v_and_b32_e32 v33, 0xffff0000, v54
	v_lshlrev_b32_e32 v34, 16, v55
	v_and_b32_e32 v35, 0xffff0000, v55
	v_lshlrev_b32_e32 v26, 16, v51
	v_and_b32_e32 v27, 0xffff0000, v51
	global_load_dwordx4 v[48:51], v[24:25], off offset:2096
	global_load_dwordx4 v[52:55], v[24:25], off offset:2080
	global_load_dwordx4 v[56:59], v[24:25], off offset:2064
	global_load_dwordx4 v[60:63], v[24:25], off offset:2048
	v_pk_fma_f32 v[28:29], v[124:125], v[134:135], v[28:29] op_sel_hi:[0,1,1]
	v_pk_fma_f32 v[32:33], v[124:125], v[138:139], v[32:33] op_sel_hi:[0,1,1]
	v_pk_fma_f32 v[34:35], v[124:125], v[140:141], v[34:35] op_sel_hi:[0,1,1]
	v_pk_fma_f32 v[38:39], v[124:125], v[144:145], v[38:39] op_sel_hi:[0,1,1]
	v_pk_fma_f32 v[42:43], v[124:125], v[148:149], v[26:27] op_sel_hi:[0,1,1]
	v_cvt_pk_bf16_f32 v24, v28, v29
	v_cvt_pk_bf16_f32 v25, v30, v31
	v_cvt_pk_bf16_f32 v26, v32, v33
	v_cvt_pk_bf16_f32 v27, v34, v35
	v_add_u32_e32 v28, v163, v168
	ds_write_b128 v28, v[24:27] offset:51200
	v_cvt_pk_bf16_f32 v24, v36, v37
	v_cvt_pk_bf16_f32 v25, v38, v39
	v_cvt_pk_bf16_f32 v26, v40, v41
	v_cvt_pk_bf16_f32 v27, v42, v43
	v_add_u32_e32 v29, v163, v169
	ds_write_b128 v29, v[24:27] offset:51200
	s_waitcnt vmcnt(13)
	ds_write_b128 v164, v[0:3] offset:18432
	s_waitcnt vmcnt(12)
	ds_write_b128 v165, v[4:7] offset:18432
	s_waitcnt vmcnt(11)
	ds_write_b128 v164, v[8:11] offset:22528
	s_waitcnt vmcnt(10)
	ds_write_b128 v166, v[12:15] offset:18432
	s_waitcnt vmcnt(9)
	ds_write_b128 v28, v[16:19]
	v_add_u32_e32 v0, v163, v171
	v_add_u32_e32 v36, v167, v170
	s_mov_b32 s3, 0x5040100
	s_waitcnt vmcnt(8)
	ds_write_b128 v0, v[20:23]
	s_waitcnt lgkmcnt(0)
	s_barrier
	ds_read_b128 v[0:3], v36 offset:51200
	ds_read_b128 v[16:19], v36 offset:51232
	s_waitcnt vmcnt(7) lgkmcnt(1)
	v_mfma_f32_32x32x16_bf16 v[0:15], v[0:3], v[64:67], 0
	s_waitcnt vmcnt(6) lgkmcnt(0)
	v_mfma_f32_32x32x16_bf16 v[0:15], v[16:19], v[68:71], v[0:15]
	ds_read_b128 v[16:19], v36 offset:51264
	ds_read_b128 v[20:23], v36 offset:51296
	s_waitcnt vmcnt(5) lgkmcnt(1)
	v_mfma_f32_32x32x16_bf16 v[0:15], v[16:19], v[72:75], v[0:15]
	ds_read_b128 v[16:19], v36 offset:55808
	ds_read_b128 v[32:35], v36 offset:55840
	s_waitcnt vmcnt(4) lgkmcnt(2)
	v_mfma_f32_32x32x16_bf16 v[0:15], v[20:23], v[76:79], v[0:15]
	s_waitcnt lgkmcnt(1)
	v_mfma_f32_32x32x16_bf16 v[16:31], v[16:19], v[64:67], 0
	s_nop 9
	v_mul_f32_e64 v14, v132, v14
	v_mul_f32_e64 v15, v133, v15
	v_mul_f32_e64 v12, v130, v12
	v_mul_f32_e64 v13, v131, v13
	v_mul_f32_e64 v10, v128, v10
	v_mul_f32_e64 v11, v129, v11
	v_pk_mul_f32 v[8:9], v[110:111], v[8:9]
	v_pk_mul_f32 v[6:7], v[108:109], v[6:7]
	v_pk_mul_f32 v[4:5], v[106:107], v[4:5]
	v_pk_mul_f32 v[2:3], v[104:105], v[2:3]
	s_waitcnt lgkmcnt(0)
	v_mfma_f32_32x32x16_bf16 v[16:31], v[32:35], v[68:71], v[16:31]
	ds_read_b128 v[32:35], v36 offset:55872
	ds_read_b128 v[36:39], v36 offset:55904
	v_mul_f32_e64 v0, v102, v0
	v_mul_f32_e64 v1, v103, v1
	s_waitcnt lgkmcnt(1)
	v_mfma_f32_32x32x16_bf16 v[16:31], v[32:35], v[72:75], v[16:31]
	s_waitcnt lgkmcnt(0)
	v_mfma_f32_32x32x16_bf16 v[16:31], v[36:39], v[76:79], v[16:31]
	s_nop 11
	v_pk_mul_f32 v[30:31], v[132:133], v[30:31]
	v_pk_mul_f32 v[28:29], v[130:131], v[28:29]
	v_pk_mul_f32 v[26:27], v[128:129], v[26:27]
	v_pk_mul_f32 v[24:25], v[110:111], v[24:25]
	v_pk_mul_f32 v[22:23], v[108:109], v[22:23]
	v_pk_mul_f32 v[20:21], v[106:107], v[20:21]
	v_pk_mul_f32 v[18:19], v[104:105], v[18:19]
	v_pk_mul_f32 v[16:17], v[102:103], v[16:17]
.LBB0_588:
	v_add_u32_e32 v113, v161, v159
	v_sub_u32_e32 v115, v159, v89
	v_sub_u32_e32 v124, v159, v88
	v_sub_u32_e32 v138, v159, v91
	v_sub_u32_e32 v139, v159, v90
	v_sub_u32_e32 v140, v159, v93
	v_sub_u32_e32 v141, v159, v92
	v_sub_u32_e32 v142, v159, v95
	v_sub_u32_e32 v143, v159, v94
	v_cvt_f32_u32_e32 v39, v113
	v_cvt_f32_u32_e32 v40, v124
	v_cvt_f32_u32_e32 v41, v115
	v_cvt_f32_u32_e32 v42, v139
	v_cvt_f32_u32_e32 v43, v138
	v_cvt_f32_u32_e32 v44, v141
	v_cvt_f32_u32_e32 v45, v140
	v_cvt_f32_u32_e32 v46, v143
	v_cvt_f32_u32_e32 v47, v142
	ds_read_b128 v[32:35], v162
	ds_read_b128 v[84:87], v162 offset:32
	ds_read_b128 v[102:105], v162 offset:64
	ds_read_b128 v[106:109], v162 offset:96
	v_add_u32_e32 v36, 0xffffdc00, v160
	v_add_u32_e32 v37, 0xfffffc00, v160
	v_add_u32_e32 v38, 0xffffe000, v160
	ds_read_b64_tr_b16 v[120:121], v36
	ds_read_b64_tr_b16 v[122:123], v36 offset:512
	ds_read_b64_tr_b16 v[116:117], v37
	ds_read_b64_tr_b16 v[118:119], v37 offset:512
	s_waitcnt lgkmcnt(0)
	ds_read_b64_tr_b16 v[130:131], v38
	ds_read_b64_tr_b16 v[132:133], v38 offset:512
	ds_read_b64_tr_b16 v[126:127], v160
	ds_read_b64_tr_b16 v[128:129], v160 offset:512
	s_waitcnt lgkmcnt(0)
	v_mul_f32_e32 v154, v151, v39
	v_mul_f32_e32 v155, v151, v40
	v_mul_f32_e32 v163, v151, v41
	v_mul_f32_e32 v164, v151, v42
	v_mul_f32_e32 v165, v151, v43
	v_mul_f32_e32 v166, v151, v44
	v_mul_f32_e32 v167, v151, v45
	v_mul_f32_e32 v168, v151, v46
	v_mul_f32_e32 v169, v151, v47
	s_waitcnt lgkmcnt(3)
	v_mfma_f32_32x32x16_bf16 v[32:47], v[32:35], v[64:67], 0
	v_add_u32_e32 v152, -1, v113
	v_sub_u32_e32 v144, v159, v97
	v_sub_u32_e32 v145, v159, v96
	v_sub_u32_e32 v146, v159, v99
	v_sub_u32_e32 v147, v159, v98
	v_sub_u32_e32 v148, v159, v101
	v_sub_u32_e32 v149, v159, v100
	s_waitcnt lgkmcnt(2)
	v_mfma_f32_32x32x16_bf16 v[32:47], v[84:87], v[68:71], v[32:47]
	v_cvt_f32_u32_e32 v153, v152
	v_cvt_f32_u32_e32 v110, v145
	v_cvt_f32_u32_e32 v111, v144
	v_cvt_f32_u32_e32 v134, v147
	v_cvt_f32_u32_e32 v135, v146
	v_cvt_f32_u32_e32 v136, v149
	v_cvt_f32_u32_e32 v137, v148
	s_waitcnt lgkmcnt(1)
	v_mfma_f32_32x32x16_bf16 v[32:47], v[102:105], v[72:75], v[32:47]
	v_mul_f32_e32 v153, v151, v153
	v_mul_f32_e32 v170, v151, v110
	v_mul_f32_e32 v171, v151, v111
	v_mul_f32_e32 v173, v151, v134
	v_mul_f32_e32 v174, v151, v135
	v_mul_f32_e32 v136, v151, v136
	v_mul_f32_e32 v137, v151, v137
	s_waitcnt lgkmcnt(0)
	v_mfma_f32_32x32x16_bf16 v[32:47], v[106:109], v[76:79], v[32:47]
	v_exp_f32_e32 v154, v154
	v_exp_f32_e32 v110, v155
	v_exp_f32_e32 v111, v163
	v_exp_f32_e32 v84, v164
	v_exp_f32_e32 v85, v165
	v_exp_f32_e32 v86, v166
	v_exp_f32_e32 v87, v167
	v_exp_f32_e32 v153, v153
	v_exp_f32_e32 v134, v168
	v_exp_f32_e32 v135, v169
	v_exp_f32_e32 v102, v170
	v_exp_f32_e32 v103, v171
	v_exp_f32_e32 v104, v173
	v_exp_f32_e32 v105, v174
	v_exp_f32_e32 v136, v136
	v_exp_f32_e32 v137, v137
	v_mul_f32_e32 v106, v154, v32
	v_mul_f32_e32 v107, v153, v33
	v_cmp_lt_i32_e32 vcc, -1, v152
	v_pk_mul_f32 v[32:33], v[110:111], v[34:35]
	v_pk_mul_f32 v[34:35], v[84:85], v[36:37]
	v_pk_mul_f32 v[36:37], v[86:87], v[38:39]
	v_pk_mul_f32 v[38:39], v[134:135], v[40:41]
	v_pk_mul_f32 v[40:41], v[102:103], v[42:43]
	v_pk_mul_f32 v[42:43], v[104:105], v[44:45]
	v_pk_mul_f32 v[44:45], v[136:137], v[46:47]
	v_cmp_lt_i32_e64 s[0:1], -1, v113
	v_cndmask_b32_e32 v47, 0, v107, vcc
	v_cvt_pk_bf16_f32 v33, v32, v33
	v_cmp_lt_i32_e32 vcc, -1, v124
	v_cvt_pk_bf16_f32 v34, v34, v35
	v_cvt_pk_bf16_f32 v35, v36, v37
	v_cndmask_b32_e64 v46, 0, v106, s[0:1]
	v_cmp_lt_i32_e64 s[0:1], -1, v139
	v_cmp_lt_i32_e64 s[4:5], -1, v141
	v_cvt_pk_bf16_f32 v36, v38, v39
	v_cvt_pk_bf16_f32 v37, v40, v41
	v_cvt_pk_bf16_f32 v39, v44, v45
	v_lshrrev_b32_e32 v40, 16, v34
	v_cmp_lt_i32_e64 s[14:15], -1, v138
	v_lshrrev_b32_e32 v41, 16, v35
	v_cmp_lt_i32_e64 s[16:17], -1, v140
	v_cndmask_b32_e32 v45, 0, v33, vcc
	v_lshrrev_b32_e32 v33, 16, v33
	v_cmp_lt_i32_e32 vcc, -1, v115
	v_cndmask_b32_e64 v34, 0, v34, s[0:1]
	v_cndmask_b32_e64 v35, 0, v35, s[4:5]
	v_cndmask_b32_e32 v33, 0, v33, vcc
	v_cndmask_b32_e64 v40, 0, v40, s[14:15]
	v_cndmask_b32_e64 v41, 0, v41, s[16:17]
	v_cvt_pk_bf16_f32 v32, v46, v47
	v_perm_b32 v33, v33, v45, s3
	v_perm_b32 v34, v40, v34, s3
	v_perm_b32 v35, v41, v35, s3
	v_cmp_lt_i32_e64 s[6:7], -1, v143
	v_cvt_pk_bf16_f32 v38, v42, v43
	v_mfma_f32_32x32x16_bf16 v[0:15], v[120:123], v[32:35], v[0:15]
	v_cmp_lt_i32_e64 s[8:9], -1, v145
	v_cmp_lt_i32_e64 s[10:11], -1, v147
	v_cmp_lt_i32_e64 s[12:13], -1, v149
	v_lshrrev_b32_e32 v42, 16, v37
	v_cmp_lt_i32_e64 s[18:19], -1, v144
	v_lshrrev_b32_e32 v43, 16, v38
	v_cmp_lt_i32_e64 s[20:21], -1, v146
	v_mfma_f32_32x32x16_bf16 v[16:31], v[116:119], v[32:35], v[16:31]
	v_lshrrev_b32_e32 v44, 16, v39
	v_cmp_lt_i32_e64 s[22:23], -1, v148
	v_cndmask_b32_e64 v40, 0, v36, s[6:7]
	v_lshrrev_b32_e32 v36, 16, v36
	v_cmp_lt_i32_e32 vcc, -1, v142
	v_cndmask_b32_e64 v37, 0, v37, s[8:9]
	v_cndmask_b32_e64 v38, 0, v38, s[10:11]
	v_cndmask_b32_e64 v39, 0, v39, s[12:13]
	v_cndmask_b32_e32 v36, 0, v36, vcc
	v_cndmask_b32_e64 v33, 0, v42, s[18:19]
	v_cndmask_b32_e64 v34, 0, v43, s[20:21]
	v_cndmask_b32_e64 v35, 0, v44, s[22:23]
	v_perm_b32 v32, v36, v40, s3
	v_perm_b32 v33, v33, v37, s3
	v_perm_b32 v34, v34, v38, s3
	v_perm_b32 v35, v35, v39, s3
	s_add_i32 s2, s2, -1
	v_subrev_u32_e32 v159, 32, v159
	v_mfma_f32_32x32x16_bf16 v[0:15], v[130:133], v[32:35], v[0:15]
	v_add_u32_e32 v162, 0x1200, v162
	s_cmp_lg_u32 s2, 0
	v_add_u32_e32 v160, 0x800, v160
	v_mfma_f32_32x32x16_bf16 v[16:31], v[126:129], v[32:35], v[16:31]
	s_cbranch_scc1 .LBB0_588
	v_lshlrev_b64 v[32:33], 12, v[82:83]
	v_readlane_b32 s4, v254, 0
	v_lshlrev_b32_e32 v36, 11, v82
	v_and_b32_e32 v32, 0xfff00000, v32
	v_readlane_b32 s6, v254, 2
	v_readlane_b32 s7, v254, 3
	s_waitcnt vmcnt(0)
	v_lshlrev_b32_e32 v40, 16, v62
	v_and_b32_e32 v38, 0xffff0000, v62
	v_lshl_add_u64 v[34:35], s[6:7], 0, v[32:33]
	v_and_b32_e32 v32, 0x7f800, v36
	v_mul_f32_e32 v36, 0xbfb8aa3b, v40
	v_mul_f32_e32 v37, 0xbfb8aa3b, v38
	v_exp_f32_e32 v36, v36
	v_exp_f32_e32 v37, v37
	v_mov_b32_e32 v33, 0
	v_lshl_add_u64 v[34:35], v[34:35], 0, v[32:33]
	v_lshlrev_b32_e32 v45, 16, v61
	v_pk_add_f32 v[36:37], v[36:37], 1.0 op_sel_hi:[1,0]
	v_and_b32_e32 v46, 0xffff0000, v61
	v_lshlrev_b32_e32 v66, 16, v63
	v_and_b32_e32 v44, 0xffff0000, v63
	v_lshlrev_b32_e32 v71, 16, v58
	v_rcp_f32_e32 v32, v37
	s_nop 0
	v_mul_f32_e32 v37, v38, v32
	v_mul_f32_e32 v38, 0xbfb8aa3b, v45
	v_mul_f32_e32 v39, 0xbfb8aa3b, v46
	v_exp_f32_e32 v38, v38
	v_exp_f32_e32 v39, v39
	s_nop 0
	v_pk_add_f32 v[38:39], v[38:39], 1.0 op_sel_hi:[1,0]
	v_rcp_f32_e32 v32, v36
	s_nop 0
	v_mul_f32_e32 v36, v40, v32
	v_and_b32_e32 v58, 0xffff0000, v58
	v_rcp_f32_e32 v32, v39
	s_nop 0
	v_mul_f32_e32 v39, v46, v32
	v_lshlrev_b32_e32 v78, 16, v59
	v_lshlrev_b32_e32 v42, 16, v60
	v_and_b32_e32 v43, 0xffff0000, v60
	v_mul_f32_e32 v40, 0xbfb8aa3b, v42
	v_mul_f32_e32 v41, 0xbfb8aa3b, v43
	v_exp_f32_e32 v40, v40
	v_exp_f32_e32 v41, v41
	v_rcp_f32_e32 v32, v38
	s_nop 0
	v_mul_f32_e32 v38, v45, v32
	v_and_b32_e32 v76, 0xffff0000, v59
	v_lshlrev_b32_e32 v77, 16, v57
	v_pk_add_f32 v[40:41], v[40:41], 1.0 op_sel_hi:[1,0]
	v_and_b32_e32 v57, 0xffff0000, v57
	v_div_scale_f32 v67, s[0:1], v41, v41, v43
	v_rcp_f32_e32 v68, v67
	s_waitcnt lgkmcnt(0)
	s_barrier
	v_rcp_f32_e32 v45, v41
	s_nop 0
	v_mul_f32_e32 v41, v43, v45
	ds_write2_b32 v172, v0, v1 offset1:1
	ds_write2_b32 v172, v2, v3 offset0:2 offset1:3
	ds_write2_b32 v172, v4, v5 offset0:8 offset1:9
	ds_write2_b32 v172, v6, v7 offset0:10 offset1:11
	ds_write2_b32 v172, v8, v9 offset0:16 offset1:17
	ds_write2_b32 v172, v10, v11 offset0:18 offset1:19
	ds_write2_b32 v172, v12, v13 offset0:24 offset1:25
	ds_write2_b32 v172, v14, v15 offset0:26 offset1:27
	ds_write2_b32 v172, v16, v17 offset0:40 offset1:41
	ds_write2_b32 v172, v18, v19 offset0:42 offset1:43
	ds_write2_b32 v172, v20, v21 offset0:48 offset1:49
	ds_write2_b32 v172, v22, v23 offset0:50 offset1:51
	ds_write2_b32 v172, v24, v25 offset0:56 offset1:57
	ds_write2_b32 v172, v26, v27 offset0:58 offset1:59
	ds_write2_b32 v172, v28, v29 offset0:64 offset1:65
	ds_write2_b32 v172, v30, v31 offset0:66 offset1:67
	v_rcp_f32_e32 v43, v40
	s_nop 0
	v_mul_f32_e32 v40, v42, v43
	v_mul_f32_e32 v42, 0xbfb8aa3b, v66
	v_mul_f32_e32 v43, 0xbfb8aa3b, v44
	v_exp_f32_e32 v42, v42
	v_exp_f32_e32 v43, v43
	s_waitcnt lgkmcnt(0)
	s_barrier
	v_pk_add_f32 v[42:43], v[42:43], 1.0 op_sel_hi:[1,0]
	v_lshlrev_b32_e32 v79, 16, v56
	global_load_dwordx4 v[16:19], v[80:81], off offset:48
	global_load_dwordx4 v[20:23], v[80:81], off offset:32
	global_load_dwordx4 v[24:27], v[80:81], off offset:16
	global_load_dwordx4 v[28:31], v[80:81], off
	global_load_dwordx4 v[0:3], v[80:81], off offset:112
	global_load_dwordx4 v[4:7], v[80:81], off offset:96
	global_load_dwordx4 v[8:11], v[80:81], off offset:80
	global_load_dwordx4 v[12:15], v[80:81], off offset:64
	v_and_b32_e32 v80, 0xffff0000, v56
	v_mul_f32_e32 v56, 0xbfb8aa3b, v79
	v_rcp_f32_e32 v45, v43
	s_nop 0
	v_mul_f32_e32 v43, v44, v45
	v_mul_f32_e32 v44, 0xbfb8aa3b, v71
	v_mul_f32_e32 v45, 0xbfb8aa3b, v58
	v_exp_f32_e32 v44, v44
	v_exp_f32_e32 v45, v45
	v_rcp_f32_e32 v67, v42
	s_nop 0
	v_mul_f32_e32 v42, v66, v67
	v_pk_add_f32 v[44:45], v[44:45], 1.0 op_sel_hi:[1,0]
	v_lshlrev_b32_e32 v83, 16, v54
	v_and_b32_e32 v54, 0xffff0000, v54
	v_lshlrev_b32_e32 v113, 16, v55
	v_and_b32_e32 v124, 0xffff0000, v55
	v_rcp_f32_e32 v59, v45
	s_nop 0
	v_mul_f32_e32 v45, v58, v59
	v_mul_f32_e32 v59, 0xbfb8aa3b, v57
	v_mul_f32_e32 v58, 0xbfb8aa3b, v77
	v_exp_f32_e32 v58, v58
	v_exp_f32_e32 v59, v59
	s_nop 0
	v_pk_add_f32 v[58:59], v[58:59], 1.0 op_sel_hi:[1,0]
	v_rcp_f32_e32 v66, v44
	s_nop 0
	v_mul_f32_e32 v44, v71, v66
	v_lshlrev_b32_e32 v88, 16, v53
	v_rcp_f32_e32 v66, v59
	s_nop 0
	v_mul_f32_e32 v57, v57, v66
	v_and_b32_e32 v53, 0xffff0000, v53
	v_exp_f32_e32 v66, v56
	v_mul_f32_e32 v56, 0xbfb8aa3b, v80
	v_exp_f32_e32 v67, v56
	v_rcp_f32_e32 v56, v58
	s_nop 0
	v_mul_f32_e32 v56, v77, v56
	v_lshlrev_b32_e32 v89, 16, v52
	ds_read2_b32 v[46:47], v158 offset0:6 offset1:7
	ds_read2_b32 v[60:61], v158 offset0:4 offset1:5
	ds_read2_b32 v[62:63], v158 offset0:2 offset1:3
	ds_read2_b32 v[64:65], v158 offset1:1
	v_pk_add_f32 v[66:67], v[66:67], 1.0 op_sel_hi:[1,0]
	ds_read2_b32 v[68:69], v158 offset0:14 offset1:15
	ds_read2_b32 v[70:71], v158 offset0:12 offset1:13
	ds_read2_b32 v[72:73], v158 offset0:10 offset1:11
	ds_read2_b32 v[74:75], v158 offset0:8 offset1:9
	s_waitcnt lgkmcnt(4)
	v_add_f32_e32 v32, 0, v64
	v_add_f32_e32 v32, v32, v65
	v_add_f32_e32 v32, v32, v62
	v_rcp_f32_e32 v59, v67
	s_nop 0
	v_mul_f32_e32 v59, v80, v59
	v_add_f32_e32 v32, v32, v63
	v_rcp_f32_e32 v58, v66
	s_nop 0
	v_mul_f32_e32 v58, v79, v58
	v_mul_f32_e32 v66, 0xbfb8aa3b, v78
	v_mul_f32_e32 v67, 0xbfb8aa3b, v76
	v_exp_f32_e32 v66, v66
	v_exp_f32_e32 v67, v67
	v_add_f32_e32 v32, v32, v60
	v_add_f32_e32 v32, v32, v61
	v_add_f32_e32 v32, v32, v46
	v_pk_add_f32 v[66:67], v[66:67], 1.0 op_sel_hi:[1,0]
	v_add_f32_e32 v32, v32, v47
	s_waitcnt lgkmcnt(0)
	v_add_f32_e32 v32, v32, v74
	v_add_f32_e32 v32, v32, v75
	v_add_f32_e32 v32, v32, v72
	v_rcp_f32_e32 v77, v67
	s_nop 0
	v_mul_f32_e32 v67, v76, v77
	v_mul_f32_e32 v76, 0xbfb8aa3b, v83
	v_mul_f32_e32 v77, 0xbfb8aa3b, v54
	v_exp_f32_e32 v76, v76
	v_exp_f32_e32 v77, v77
	v_rcp_f32_e32 v79, v66
	s_nop 0
	v_mul_f32_e32 v66, v78, v79
	v_pk_add_f32 v[76:77], v[76:77], 1.0 op_sel_hi:[1,0]
	v_add_f32_e32 v32, v32, v73
	v_add_f32_e32 v32, v32, v70
	v_add_f32_e32 v32, v32, v71
	v_add_f32_e32 v32, v32, v68
	v_mul_f32_e32 v78, 0xbfb8aa3b, v88
	v_mul_f32_e32 v79, 0xbfb8aa3b, v53
	v_rcp_f32_e32 v55, v77
	s_nop 0
	v_mul_f32_e32 v55, v54, v55
	v_exp_f32_e32 v78, v78
	v_exp_f32_e32 v79, v79
	s_nop 0
	v_pk_add_f32 v[78:79], v[78:79], 1.0 op_sel_hi:[1,0]
	v_rcp_f32_e32 v54, v76
	s_nop 0
	v_mul_f32_e32 v54, v83, v54
	v_add_f32_e32 v32, v32, v69
	v_rcp_f32_e32 v77, v79
	s_nop 0
	v_mul_f32_e32 v77, v53, v77
	s_mov_b32 s37, 0
	v_and_b32_e32 v79, 0xffff0000, v52
	v_mul_f32_e32 v52, 0xbfb8aa3b, v89
	v_mul_f32_e32 v53, 0xbfb8aa3b, v79
	v_exp_f32_e32 v52, v52
	v_exp_f32_e32 v53, v53
	v_rcp_f32_e32 v76, v78
	s_nop 0
	v_mul_f32_e32 v76, v88, v76
	ds_read2_b32 v[80:81], v158 offset0:22 offset1:23
	ds_read2_b32 v[82:83], v158 offset0:20 offset1:21
	ds_read2_b32 v[84:85], v158 offset0:18 offset1:19
	ds_read2_b32 v[86:87], v158 offset0:16 offset1:17
	v_lshl_add_u64 v[34:35], v[34:35], 0, s[36:37]
	v_pk_add_f32 v[52:53], v[52:53], 1.0 op_sel_hi:[1,0]
	v_mov_b32_e32 v115, v33
	s_waitcnt lgkmcnt(0)
	v_add_f32_e32 v32, v32, v86
	v_add_f32_e32 v32, v32, v87
	v_add_f32_e32 v32, v32, v84
	v_rcp_f32_e32 v78, v53
	s_nop 0
	v_mul_f32_e32 v79, v79, v78
	v_add_f32_e32 v32, v32, v85
	v_rcp_f32_e32 v78, v52
	s_nop 0
	v_mul_f32_e32 v78, v89, v78
	v_mul_f32_e32 v52, 0xbfb8aa3b, v113
	v_mul_f32_e32 v53, 0xbfb8aa3b, v124
	v_exp_f32_e32 v52, v52
	v_exp_f32_e32 v53, v53
	v_add_f32_e32 v32, v32, v82
	v_add_f32_e32 v32, v32, v83
	v_add_f32_e32 v32, v32, v80
	v_pk_add_f32 v[88:89], v[52:53], 1.0 op_sel_hi:[1,0]
	ds_read2_b32 v[90:91], v158 offset0:30 offset1:31
	ds_read2_b32 v[52:53], v158 offset0:28 offset1:29
	ds_read2_b32 v[92:93], v158 offset0:26 offset1:27
	ds_read2_b32 v[94:95], v158 offset0:24 offset1:25
	v_add_f32_e32 v32, v32, v81
	s_waitcnt lgkmcnt(0)
	v_add_f32_e32 v32, v32, v94
	v_add_f32_e32 v32, v32, v95
	v_add_f32_e32 v32, v32, v92
	v_add_f32_e32 v32, v32, v93
	v_add_f32_e32 v32, v32, v52
	v_add_f32_e32 v32, v32, v53
	v_add_f32_e32 v32, v32, v90
	v_add_f32_e32 v32, v32, v91
	s_nop 1
	v_add_f32_dpp v32, v32, v32 quad_perm:[1,0,3,2] row_mask:0xf bank_mask:0xf
	s_waitcnt lgkmcnt(0)
	s_nop 1
	v_add_f32_dpp v32, v32, v32 quad_perm:[2,3,0,1] row_mask:0xf bank_mask:0xf
	v_lshl_add_u64 v[34:35], v[34:35], 0, v[114:115]
	s_waitcnt lgkmcnt(0)
	v_mul_f32_e32 v32, 0x3c000000, v32
	v_pk_add_f32 v[64:65], v[64:65], v[32:33] op_sel_hi:[1,0] neg_lo:[0,1] neg_hi:[0,1]
	v_pk_add_f32 v[62:63], v[62:63], v[32:33] op_sel_hi:[1,0] neg_lo:[0,1] neg_hi:[0,1]
	v_pk_mul_f32 v[96:97], v[64:65], v[64:65]
	v_pk_mul_f32 v[98:99], v[62:63], v[62:63]
	v_pk_add_f32 v[100:101], v[60:61], v[32:33] op_sel_hi:[1,0] neg_lo:[0,1] neg_hi:[0,1]
	v_pk_add_f32 v[104:105], v[46:47], v[32:33] op_sel_hi:[1,0] neg_lo:[0,1] neg_hi:[0,1]
	v_pk_add_f32 v[74:75], v[74:75], v[32:33] op_sel_hi:[1,0] neg_lo:[0,1] neg_hi:[0,1]
	v_pk_add_f32 v[72:73], v[72:73], v[32:33] op_sel_hi:[1,0] neg_lo:[0,1] neg_hi:[0,1]
	v_pk_add_f32 v[70:71], v[70:71], v[32:33] op_sel_hi:[1,0] neg_lo:[0,1] neg_hi:[0,1]
	v_pk_add_f32 v[68:69], v[68:69], v[32:33] op_sel_hi:[1,0] neg_lo:[0,1] neg_hi:[0,1]
	v_pk_add_f32 v[86:87], v[86:87], v[32:33] op_sel_hi:[1,0] neg_lo:[0,1] neg_hi:[0,1]
	v_pk_add_f32 v[84:85], v[84:85], v[32:33] op_sel_hi:[1,0] neg_lo:[0,1] neg_hi:[0,1]
	v_pk_add_f32 v[82:83], v[82:83], v[32:33] op_sel_hi:[1,0] neg_lo:[0,1] neg_hi:[0,1]
	v_pk_add_f32 v[80:81], v[80:81], v[32:33] op_sel_hi:[1,0] neg_lo:[0,1] neg_hi:[0,1]
	v_pk_add_f32 v[94:95], v[94:95], v[32:33] op_sel_hi:[1,0] neg_lo:[0,1] neg_hi:[0,1]
	v_pk_add_f32 v[60:61], v[92:93], v[32:33] op_sel_hi:[1,0] neg_lo:[0,1] neg_hi:[0,1]
	v_pk_add_f32 v[52:53], v[52:53], v[32:33] op_sel_hi:[1,0] neg_lo:[0,1] neg_hi:[0,1]
	v_pk_add_f32 v[46:47], v[90:91], v[32:33] op_sel_hi:[1,0] neg_lo:[0,1] neg_hi:[0,1]
	v_add_f32_e32 v32, v96, v97
	v_add_f32_e32 v32, v98, v32
	v_pk_mul_f32 v[102:103], v[100:101], v[100:101]
	v_add_f32_e32 v32, v99, v32
	v_add_f32_e32 v32, v102, v32
	v_pk_mul_f32 v[106:107], v[104:105], v[104:105]
	v_add_f32_e32 v32, v103, v32
	v_add_f32_e32 v32, v106, v32
	v_pk_mul_f32 v[108:109], v[74:75], v[74:75]
	v_add_f32_e32 v32, v107, v32
	v_add_f32_e32 v32, v108, v32
	v_pk_mul_f32 v[110:111], v[72:73], v[72:73]
	v_add_f32_e32 v32, v109, v32
	v_add_f32_e32 v32, v110, v32
	v_pk_mul_f32 v[114:115], v[70:71], v[70:71]
	v_add_f32_e32 v32, v111, v32
	v_add_f32_e32 v32, v114, v32
	v_pk_mul_f32 v[116:117], v[68:69], v[68:69]
	v_add_f32_e32 v32, v115, v32
	v_add_f32_e32 v32, v116, v32
	v_pk_mul_f32 v[118:119], v[86:87], v[86:87]
	v_add_f32_e32 v32, v117, v32
	v_add_f32_e32 v32, v118, v32
	v_pk_mul_f32 v[120:121], v[84:85], v[84:85]
	v_add_f32_e32 v32, v119, v32
	v_add_f32_e32 v32, v120, v32
	v_pk_mul_f32 v[122:123], v[82:83], v[82:83]
	v_add_f32_e32 v32, v121, v32
	v_add_f32_e32 v32, v122, v32
	v_pk_mul_f32 v[126:127], v[80:81], v[80:81]
	v_add_f32_e32 v32, v123, v32
	v_add_f32_e32 v32, v126, v32
	v_pk_mul_f32 v[128:129], v[94:95], v[94:95]
	v_add_f32_e32 v32, v127, v32
	v_add_f32_e32 v32, v128, v32
	v_pk_mul_f32 v[92:93], v[60:61], v[60:61]
	v_add_f32_e32 v32, v129, v32
	v_add_f32_e32 v32, v92, v32
	v_pk_mul_f32 v[130:131], v[52:53], v[52:53]
	v_add_f32_e32 v32, v93, v32
	v_add_f32_e32 v32, v130, v32
	v_pk_mul_f32 v[90:91], v[46:47], v[46:47]
	v_add_f32_e32 v32, v131, v32
	v_add_f32_e32 v32, v90, v32
	v_add_f32_e32 v32, v91, v32
	s_nop 1
	v_add_f32_dpp v32, v32, v32 quad_perm:[1,0,3,2] row_mask:0xf bank_mask:0xf
	s_mov_b32 s0, 0xf800000
	v_rcp_f32_e32 v91, v89
	s_nop 0
	v_mul_f32_e32 v89, v124, v91
	s_waitcnt lgkmcnt(0)
	s_nop 1
	v_add_f32_dpp v32, v32, v32 quad_perm:[2,3,0,1] row_mask:0xf bank_mask:0xf
	s_waitcnt lgkmcnt(0)
	v_mov_b32_e32 v90, 0x358637bd
	v_fmac_f32_e32 v90, 0x3c000000, v32
	v_mul_f32_e32 v32, 0x4f800000, v90
	v_cmp_gt_f32_e64 s[0:1], s0, v90
	s_nop 1
	v_cndmask_b32_e64 v32, v90, v32, s[0:1]
	v_sqrt_f32_e32 v90, v32
	v_readlane_b32 s5, v254, 1
	v_add_u32_e32 v93, -1, v90
	v_fma_f32 v96, -v93, v90, v32
	v_cmp_ge_f32_e64 s[4:5], 0, v96
	v_add_u32_e32 v96, 1, v90
	s_nop 1
	v_cndmask_b32_e64 v93, v90, v93, s[4:5]
	v_fma_f32 v90, -v96, v90, v32
	v_cmp_lt_f32_e64 s[4:5], 0, v90
	v_rcp_f32_e32 v91, v88
	s_nop 0
	v_mul_f32_e32 v88, v113, v91
	s_movk_i32 s2, 0x37ff
	v_cndmask_b32_e64 v90, v93, v96, s[4:5]
	v_mul_f32_e32 v93, 0x37800000, v90
	v_cndmask_b32_e64 v90, v90, v93, s[0:1]
	v_mov_b32_e32 v93, 0x260
	v_cmp_class_f32_e64 s[0:1], v32, v93
	s_nop 1
	v_cndmask_b32_e64 v32, v90, v32, s[0:1]
	v_rcp_f32_e32 v32, v32
	s_nop 0
	v_pk_mul_f32 v[64:65], v[64:65], v[32:33] op_sel_hi:[1,0]
	s_waitcnt vmcnt(4)
	v_pk_mul_f32 v[28:29], v[28:29], v[64:65]
	s_nop 0
	v_pk_mul_f32 v[28:29], v[40:41], v[28:29]
	v_pk_mul_f32 v[40:41], v[62:63], v[32:33] op_sel_hi:[1,0]
	s_nop 0
	v_pk_mul_f32 v[30:31], v[30:31], v[40:41]
	s_nop 0
	v_pk_mul_f32 v[30:31], v[38:39], v[30:31]
	v_pk_mul_f32 v[38:39], v[100:101], v[32:33] op_sel_hi:[1,0]
	s_nop 0
	v_pk_mul_f32 v[24:25], v[24:25], v[38:39]
	s_nop 0
	v_pk_mul_f32 v[36:37], v[36:37], v[24:25]
	v_pk_mul_f32 v[24:25], v[104:105], v[32:33] op_sel_hi:[1,0]
	s_nop 0
	v_pk_mul_f32 v[24:25], v[26:27], v[24:25]
	v_cvt_pk_bf16_f32 v26, v36, v37
	v_pk_mul_f32 v[38:39], v[42:43], v[24:25]
	v_cvt_pk_bf16_f32 v24, v28, v29
	v_cvt_pk_bf16_f32 v25, v30, v31
	v_cvt_pk_bf16_f32 v27, v38, v39
	global_store_dwordx4 v[34:35], v[24:27], off
	s_nop 1
	v_pk_mul_f32 v[24:25], v[74:75], v[32:33] op_sel_hi:[1,0]
	s_nop 0
	v_pk_mul_f32 v[20:21], v[20:21], v[24:25]
	v_pk_mul_f32 v[24:25], v[72:73], v[32:33] op_sel_hi:[1,0]
	v_pk_mul_f32 v[20:21], v[58:59], v[20:21]
	v_pk_mul_f32 v[22:23], v[22:23], v[24:25]
	v_pk_mul_f32 v[24:25], v[70:71], v[32:33] op_sel_hi:[1,0]
	v_pk_mul_f32 v[22:23], v[56:57], v[22:23]
	v_pk_mul_f32 v[16:17], v[16:17], v[24:25]
	s_nop 0
	v_pk_mul_f32 v[24:25], v[44:45], v[16:17]
	v_pk_mul_f32 v[16:17], v[68:69], v[32:33] op_sel_hi:[1,0]
	s_nop 0
	v_pk_mul_f32 v[16:17], v[18:19], v[16:17]
	v_cvt_pk_bf16_f32 v18, v24, v25
	v_pk_mul_f32 v[26:27], v[66:67], v[16:17]
	v_cvt_pk_bf16_f32 v16, v20, v21
	v_cvt_pk_bf16_f32 v17, v22, v23
	v_cvt_pk_bf16_f32 v19, v26, v27
	global_store_dwordx4 v[34:35], v[16:19], off offset:16
	v_lshlrev_b32_e32 v20, 16, v48
	v_and_b32_e32 v21, 0xffff0000, v48
	v_pk_mul_f32 v[16:17], v[86:87], v[32:33] op_sel_hi:[1,0]
	s_waitcnt vmcnt(2)
	v_pk_mul_f32 v[12:13], v[12:13], v[16:17]
	v_pk_mul_f32 v[16:17], v[84:85], v[32:33] op_sel_hi:[1,0]
	v_pk_mul_f32 v[12:13], v[78:79], v[12:13]
	v_pk_mul_f32 v[14:15], v[14:15], v[16:17]
	v_pk_mul_f32 v[16:17], v[82:83], v[32:33] op_sel_hi:[1,0]
	v_pk_mul_f32 v[14:15], v[76:77], v[14:15]
	v_pk_mul_f32 v[8:9], v[8:9], v[16:17]
	s_nop 0
	v_pk_mul_f32 v[16:17], v[54:55], v[8:9]
	v_pk_mul_f32 v[8:9], v[80:81], v[32:33] op_sel_hi:[1,0]
	s_nop 0
	v_pk_mul_f32 v[8:9], v[10:11], v[8:9]
	v_mul_f32_e32 v10, 0xbfb8aa3b, v20
	v_mul_f32_e32 v11, 0xbfb8aa3b, v21
	v_exp_f32_e32 v10, v10
	v_exp_f32_e32 v11, v11
	v_pk_mul_f32 v[18:19], v[88:89], v[8:9]
	v_cvt_pk_bf16_f32 v8, v12, v13
	v_cvt_pk_bf16_f32 v9, v14, v15
	v_pk_add_f32 v[12:13], v[10:11], 1.0 op_sel_hi:[1,0]
	v_cvt_pk_bf16_f32 v10, v16, v17
	v_cvt_pk_bf16_f32 v11, v18, v19
	global_store_dwordx4 v[34:35], v[8:11], off offset:32
	v_and_b32_e32 v16, 0xffff0000, v49
	s_nop 0
	v_rcp_f32_e32 v9, v13
	s_nop 0
	v_mul_f32_e32 v9, v21, v9
	v_lshlrev_b32_e32 v15, 16, v49
	v_mul_f32_e32 v10, 0xbfb8aa3b, v15
	v_mul_f32_e32 v11, 0xbfb8aa3b, v16
	v_exp_f32_e32 v10, v10
	v_exp_f32_e32 v11, v11
	v_rcp_f32_e32 v8, v12
	s_nop 0
	v_mul_f32_e32 v8, v20, v8
	v_pk_mul_f32 v[12:13], v[94:95], v[32:33] op_sel_hi:[1,0]
	v_pk_add_f32 v[10:11], v[10:11], 1.0 op_sel_hi:[1,0]
	v_pk_mul_f32 v[4:5], v[4:5], v[12:13]
	v_pk_mul_f32 v[4:5], v[8:9], v[4:5]
	v_rcp_f32_e32 v9, v11
	s_nop 0
	v_mul_f32_e32 v9, v16, v9
	v_lshlrev_b32_e32 v16, 16, v50
	v_and_b32_e32 v17, 0xffff0000, v50
	v_mul_f32_e32 v12, 0xbfb8aa3b, v16
	v_mul_f32_e32 v13, 0xbfb8aa3b, v17
	v_exp_f32_e32 v12, v12
	v_exp_f32_e32 v13, v13
	v_rcp_f32_e32 v8, v10
	s_nop 0
	v_mul_f32_e32 v8, v15, v8
	v_pk_add_f32 v[10:11], v[12:13], 1.0 op_sel_hi:[1,0]
	s_nop 0
	v_pk_mul_f32 v[12:13], v[60:61], v[32:33] op_sel_hi:[1,0]
	s_nop 0
	v_pk_mul_f32 v[6:7], v[6:7], v[12:13]
	s_nop 0
	v_pk_mul_f32 v[6:7], v[8:9], v[6:7]
	v_rcp_f32_e32 v9, v11
	s_nop 0
	v_mul_f32_e32 v9, v17, v9
	v_lshlrev_b32_e32 v15, 16, v51
	v_and_b32_e32 v17, 0xffff0000, v51
	v_mul_f32_e32 v12, 0xbfb8aa3b, v15
	v_mul_f32_e32 v13, 0xbfb8aa3b, v17
	v_exp_f32_e32 v12, v12
	v_exp_f32_e32 v13, v13
	v_rcp_f32_e32 v8, v10
	s_nop 0
	v_mul_f32_e32 v8, v16, v8
	v_pk_add_f32 v[10:11], v[12:13], 1.0 op_sel_hi:[1,0]
	s_nop 0
	v_pk_mul_f32 v[12:13], v[52:53], v[32:33] op_sel_hi:[1,0]
	s_nop 0
	v_pk_mul_f32 v[0:1], v[0:1], v[12:13]
	s_nop 0
	v_pk_mul_f32 v[8:9], v[8:9], v[0:1]
	v_rcp_f32_e32 v1, v11
	s_nop 0
	v_mul_f32_e32 v1, v17, v1
	v_rcp_f32_e32 v0, v10
	s_nop 0
	v_mul_f32_e32 v0, v15, v0
	v_pk_mul_f32 v[10:11], v[46:47], v[32:33] op_sel_hi:[1,0]
	s_mov_b64 s[0:1], 0x3300000
	v_pk_mul_f32 v[2:3], v[2:3], v[10:11]
	s_nop 0
	v_pk_mul_f32 v[10:11], v[0:1], v[2:3]
	v_cvt_pk_bf16_f32 v0, v4, v5
	v_cvt_pk_bf16_f32 v1, v6, v7
	v_cvt_pk_bf16_f32 v2, v8, v9
	v_cvt_pk_bf16_f32 v3, v10, v11
	global_store_dwordx4 v[34:35], v[0:3], off offset:48
	v_lshl_add_u32 v5, s52, 9, v226
	s_waitcnt lgkmcnt(0)
	s_barrier
	s_lshr_b32 s0, s88, 5
	s_lshl_b32 s1, s0, 3
	s_add_i32 s1, s1, s53
	s_lshl_b32 s2, s1, 8
	s_lshl_b32 s3, s52, 3
	s_add_i32 s2, s2, s3
	v_readlane_b32 s8, v254, 2
	v_readlane_b32 s9, v254, 3
	v_lshrrev_b32_e32 v22, 6, v226
	v_add_u32_e32 v23, s2, v22
	v_and_b32_e32 v32, 63, v226
	v_lshlrev_b32_e32 v32, 4, v32
	v_bfe_u32 v33, v226, 3, 3
	v_lshlrev_b32_e32 v33, 2, v33
	v_lshl_add_u32 v0, v23, 5, v33
	v_add_u32_e32 v0, 0x3300000, v0
	v_add_u32_e32 v1, 0x1000, v0
	v_add_u32_e32 v2, 0x80000, v0
	v_add_u32_e32 v3, 0x81000, v0
	v_add_u32_e32 v4, 0x100000, v0
	v_add_u32_e32 v5, 0x101000, v0
	v_lshl_add_u32 v6, v23, 10, v32
	v_add_u32_e32 v6, 0xb500000, v6
	v_add_u32_e32 v7, s3, v22
	v_lshl_add_u32 v7, v7, 11, v32
	s_lshl_b32 s2, s1, 20
	s_add_u32 s8, s8, s2
	s_addc_u32 s9, s9, 0
	global_load_dword v60, v0, s[96:97]
	global_load_dword v61, v2, s[96:97]
	global_load_dword v62, v4, s[96:97]
	global_load_dwordx4 v[48:51], v6, s[96:97]
	v_add_u32_e32 v8, 0x1000000, v6
	global_load_dwordx4 v[52:55], v8, s[96:97]
	v_add_u32_e32 v8, 0x2000000, v6
	global_load_dwordx4 v[56:59], v8, s[96:97]
	global_load_dword v76, v0, s[96:97] offset:1024
	global_load_dword v77, v2, s[96:97] offset:1024
	global_load_dword v78, v4, s[96:97] offset:1024
	v_add_u32_e32 v8, 0x8000, v6
	global_load_dwordx4 v[64:67], v8, s[96:97]
	v_add_u32_e32 v8, 0x1008000, v6
	global_load_dwordx4 v[68:71], v8, s[96:97]
	v_add_u32_e32 v8, 0x2008000, v6
	global_load_dwordx4 v[72:75], v8, s[96:97]
	global_load_dword v92, v0, s[96:97] offset:2048
	global_load_dword v93, v2, s[96:97] offset:2048
	global_load_dword v94, v4, s[96:97] offset:2048
	v_add_u32_e32 v8, 0x10000, v6
	global_load_dwordx4 v[80:83], v8, s[96:97]
	v_add_u32_e32 v8, 0x1010000, v6
	global_load_dwordx4 v[84:87], v8, s[96:97]
	v_add_u32_e32 v8, 0x2010000, v6
	global_load_dwordx4 v[88:91], v8, s[96:97]
	global_load_dword v108, v0, s[96:97] offset:3072
	global_load_dword v109, v2, s[96:97] offset:3072
	global_load_dword v110, v4, s[96:97] offset:3072
	v_add_u32_e32 v8, 0x18000, v6
	global_load_dwordx4 v[96:99], v8, s[96:97]
	v_add_u32_e32 v8, 0x1018000, v6
	global_load_dwordx4 v[100:103], v8, s[96:97]
	v_add_u32_e32 v8, 0x2018000, v6
	global_load_dwordx4 v[104:107], v8, s[96:97]
	global_load_dword v140, v1, s[96:97]
	global_load_dword v141, v3, s[96:97]
	global_load_dword v142, v5, s[96:97]
	v_add_u32_e32 v8, 0x20000, v6
	global_load_dwordx4 v[128:131], v8, s[96:97]
	v_add_u32_e32 v8, 0x1020000, v6
	global_load_dwordx4 v[132:135], v8, s[96:97]
	v_add_u32_e32 v8, 0x2020000, v6
	global_load_dwordx4 v[136:139], v8, s[96:97]
	global_load_dword v164, v1, s[96:97] offset:1024
	global_load_dword v165, v3, s[96:97] offset:1024
	global_load_dword v166, v5, s[96:97] offset:1024
	v_add_u32_e32 v8, 0x28000, v6
	global_load_dwordx4 v[152:155], v8, s[96:97]
	v_add_u32_e32 v8, 0x1028000, v6
	global_load_dwordx4 v[156:159], v8, s[96:97]
	v_add_u32_e32 v8, 0x2028000, v6
	global_load_dwordx4 v[160:163], v8, s[96:97]
	global_load_dword v218, v1, s[96:97] offset:2048
	global_load_dword v219, v3, s[96:97] offset:2048
	global_load_dword v220, v5, s[96:97] offset:2048
	v_add_u32_e32 v8, 0x30000, v6
	global_load_dwordx4 v[206:209], v8, s[96:97]
	v_add_u32_e32 v8, 0x1030000, v6
	global_load_dwordx4 v[210:213], v8, s[96:97]
	v_add_u32_e32 v8, 0x2030000, v6
	global_load_dwordx4 v[214:217], v8, s[96:97]
	global_load_dword v244, v1, s[96:97] offset:3072
	global_load_dword v245, v3, s[96:97] offset:3072
	global_load_dword v246, v5, s[96:97] offset:3072
	v_add_u32_e32 v8, 0x38000, v6
	global_load_dwordx4 v[232:235], v8, s[96:97]
	v_add_u32_e32 v8, 0x1038000, v6
	global_load_dwordx4 v[236:239], v8, s[96:97]
	v_add_u32_e32 v8, 0x2038000, v6
	global_load_dwordx4 v[240:243], v8, s[96:97]
	s_waitcnt vmcnt(42)
	v_max3_f32 v5, v60, v61, v62
	v_sub_f32_e32 v9, v60, v5
	v_sub_f32_e32 v40, v61, v5
	v_and_b32_e32 v27, 0xffff0000, v49
	v_lshlrev_b32_e32 v28, 16, v49
	v_sub_f32_e32 v5, v62, v5
	v_lshlrev_b32_e32 v24, 16, v52
	v_and_b32_e32 v11, 0xffff0000, v52
	v_lshlrev_b32_e32 v38, 16, v56
	v_and_b32_e32 v39, 0xffff0000, v56
	v_lshlrev_b32_e32 v26, 16, v53
	v_and_b32_e32 v29, 0xffff0000, v53
	v_lshlrev_b32_e32 v14, 16, v57
	v_and_b32_e32 v15, 0xffff0000, v57
	v_lshlrev_b32_e32 v18, 16, v58
	v_and_b32_e32 v19, 0xffff0000, v58
	v_mul_f32_e32 v9, 0x3fb8aa3b, v9
	v_mul_f32_e32 v20, 0x3fb8aa3b, v40
	v_and_b32_e32 v35, 0xffff0000, v51
	v_lshlrev_b32_e32 v36, 16, v51
	v_lshlrev_b32_e32 v30, 16, v54
	v_and_b32_e32 v13, 0xffff0000, v54
	v_lshlrev_b32_e32 v34, 16, v55
	v_and_b32_e32 v37, 0xffff0000, v55
	v_lshlrev_b32_e32 v16, 16, v59
	v_and_b32_e32 v17, 0xffff0000, v59
	v_mul_f32_e32 v5, 0x3fb8aa3b, v5
	v_exp_f32_e32 v21, v9
	v_exp_f32_e32 v20, v20
	v_exp_f32_e32 v5, v5
	v_and_b32_e32 v25, 0xffff0000, v48
	v_lshlrev_b32_e32 v10, 16, v48
	v_add_f32_e32 v9, v21, v20
	v_add_f32_e32 v9, v5, v9
	v_and_b32_e32 v31, 0xffff0000, v50
	v_rcp_f32_e32 v40, v9
	s_nop 0
	v_lshlrev_b32_e32 v12, 16, v50
	v_pk_mul_f32 v[20:21], v[20:21], v[40:41] op_sel_hi:[1,0]
	v_mul_f32_e32 v42, v5, v40
	v_pk_mul_f32 v[10:11], v[20:21], v[10:11] op_sel:[1,0] op_sel_hi:[0,1]
	v_pk_mul_f32 v[28:29], v[20:21], v[28:29] op_sel:[1,0] op_sel_hi:[0,1]
	v_pk_mul_f32 v[12:13], v[20:21], v[12:13] op_sel:[1,0] op_sel_hi:[0,1]
	v_pk_mul_f32 v[36:37], v[20:21], v[36:37] op_sel:[1,0] op_sel_hi:[0,1]
	v_pk_fma_f32 v[10:11], v[20:21], v[24:25], v[10:11]
	v_pk_fma_f32 v[24:25], v[20:21], v[26:27], v[28:29]
	v_pk_fma_f32 v[12:13], v[20:21], v[30:31], v[12:13]
	v_pk_fma_f32 v[20:21], v[20:21], v[34:35], v[36:37]
	v_pk_fma_f32 v[10:11], v[42:43], v[38:39], v[10:11] op_sel_hi:[0,1,1]
	v_pk_fma_f32 v[14:15], v[42:43], v[14:15], v[24:25] op_sel_hi:[0,1,1]
	v_pk_fma_f32 v[12:13], v[42:43], v[18:19], v[12:13] op_sel_hi:[0,1,1]
	v_pk_fma_f32 v[16:17], v[42:43], v[16:17], v[20:21] op_sel_hi:[0,1,1]
	v_cvt_pk_bf16_f32 v10, v10, v11
	v_cvt_pk_bf16_f32 v11, v14, v15
	v_cvt_pk_bf16_f32 v12, v12, v13
	v_cvt_pk_bf16_f32 v13, v16, v17
	global_store_dwordx4 v7, v[10:13], s[8:9] offset:1024
	s_waitcnt vmcnt(37)
	v_max3_f32 v5, v76, v77, v78
	v_sub_f32_e32 v9, v76, v5
	v_sub_f32_e32 v40, v77, v5
	v_and_b32_e32 v27, 0xffff0000, v65
	v_lshlrev_b32_e32 v28, 16, v65
	v_sub_f32_e32 v5, v78, v5
	v_lshlrev_b32_e32 v24, 16, v68
	v_and_b32_e32 v11, 0xffff0000, v68
	v_lshlrev_b32_e32 v38, 16, v72
	v_and_b32_e32 v39, 0xffff0000, v72
	v_lshlrev_b32_e32 v26, 16, v69
	v_and_b32_e32 v29, 0xffff0000, v69
	v_lshlrev_b32_e32 v14, 16, v73
	v_and_b32_e32 v15, 0xffff0000, v73
	v_lshlrev_b32_e32 v18, 16, v74
	v_and_b32_e32 v19, 0xffff0000, v74
	v_mul_f32_e32 v9, 0x3fb8aa3b, v9
	v_mul_f32_e32 v20, 0x3fb8aa3b, v40
	v_and_b32_e32 v35, 0xffff0000, v67
	v_lshlrev_b32_e32 v36, 16, v67
	v_lshlrev_b32_e32 v30, 16, v70
	v_and_b32_e32 v13, 0xffff0000, v70
	v_lshlrev_b32_e32 v34, 16, v71
	v_and_b32_e32 v37, 0xffff0000, v71
	v_lshlrev_b32_e32 v16, 16, v75
	v_and_b32_e32 v17, 0xffff0000, v75
	v_mul_f32_e32 v5, 0x3fb8aa3b, v5
	v_exp_f32_e32 v21, v9
	v_exp_f32_e32 v20, v20
	v_exp_f32_e32 v5, v5
	v_and_b32_e32 v25, 0xffff0000, v64
	v_lshlrev_b32_e32 v10, 16, v64
	v_add_f32_e32 v9, v21, v20
	v_add_f32_e32 v9, v5, v9
	v_and_b32_e32 v31, 0xffff0000, v66
	v_rcp_f32_e32 v40, v9
	s_nop 0
	v_lshlrev_b32_e32 v12, 16, v66
	v_pk_mul_f32 v[20:21], v[20:21], v[40:41] op_sel_hi:[1,0]
	v_mul_f32_e32 v42, v5, v40
	v_pk_mul_f32 v[10:11], v[20:21], v[10:11] op_sel:[1,0] op_sel_hi:[0,1]
	v_pk_mul_f32 v[28:29], v[20:21], v[28:29] op_sel:[1,0] op_sel_hi:[0,1]
	v_pk_mul_f32 v[12:13], v[20:21], v[12:13] op_sel:[1,0] op_sel_hi:[0,1]
	v_pk_mul_f32 v[36:37], v[20:21], v[36:37] op_sel:[1,0] op_sel_hi:[0,1]
	v_pk_fma_f32 v[10:11], v[20:21], v[24:25], v[10:11]
	v_pk_fma_f32 v[24:25], v[20:21], v[26:27], v[28:29]
	v_pk_fma_f32 v[12:13], v[20:21], v[30:31], v[12:13]
	v_pk_fma_f32 v[20:21], v[20:21], v[34:35], v[36:37]
	v_pk_fma_f32 v[10:11], v[42:43], v[38:39], v[10:11] op_sel_hi:[0,1,1]
	v_pk_fma_f32 v[14:15], v[42:43], v[14:15], v[24:25] op_sel_hi:[0,1,1]
	v_pk_fma_f32 v[12:13], v[42:43], v[18:19], v[12:13] op_sel_hi:[0,1,1]
	v_pk_fma_f32 v[16:17], v[42:43], v[16:17], v[20:21] op_sel_hi:[0,1,1]
	v_cvt_pk_bf16_f32 v10, v10, v11
	v_cvt_pk_bf16_f32 v11, v14, v15
	v_cvt_pk_bf16_f32 v12, v12, v13
	v_cvt_pk_bf16_f32 v13, v16, v17
	v_add_u32_e32 v8, 0x10000, v7
	global_store_dwordx4 v8, v[10:13], s[8:9] offset:1024
	s_waitcnt vmcnt(32)
	v_max3_f32 v5, v92, v93, v94
	v_sub_f32_e32 v9, v92, v5
	v_sub_f32_e32 v40, v93, v5
	v_and_b32_e32 v27, 0xffff0000, v81
	v_lshlrev_b32_e32 v28, 16, v81
	v_sub_f32_e32 v5, v94, v5
	v_lshlrev_b32_e32 v24, 16, v84
	v_and_b32_e32 v11, 0xffff0000, v84
	v_lshlrev_b32_e32 v38, 16, v88
	v_and_b32_e32 v39, 0xffff0000, v88
	v_lshlrev_b32_e32 v26, 16, v85
	v_and_b32_e32 v29, 0xffff0000, v85
	v_lshlrev_b32_e32 v14, 16, v89
	v_and_b32_e32 v15, 0xffff0000, v89
	v_lshlrev_b32_e32 v18, 16, v90
	v_and_b32_e32 v19, 0xffff0000, v90
	v_mul_f32_e32 v9, 0x3fb8aa3b, v9
	v_mul_f32_e32 v20, 0x3fb8aa3b, v40
	v_and_b32_e32 v35, 0xffff0000, v83
	v_lshlrev_b32_e32 v36, 16, v83
	v_lshlrev_b32_e32 v30, 16, v86
	v_and_b32_e32 v13, 0xffff0000, v86
	v_lshlrev_b32_e32 v34, 16, v87
	v_and_b32_e32 v37, 0xffff0000, v87
	v_lshlrev_b32_e32 v16, 16, v91
	v_and_b32_e32 v17, 0xffff0000, v91
	v_mul_f32_e32 v5, 0x3fb8aa3b, v5
	v_exp_f32_e32 v21, v9
	v_exp_f32_e32 v20, v20
	v_exp_f32_e32 v5, v5
	v_and_b32_e32 v25, 0xffff0000, v80
	v_lshlrev_b32_e32 v10, 16, v80
	v_add_f32_e32 v9, v21, v20
	v_add_f32_e32 v9, v5, v9
	v_and_b32_e32 v31, 0xffff0000, v82
	v_rcp_f32_e32 v40, v9
	s_nop 0
	v_lshlrev_b32_e32 v12, 16, v82
	v_pk_mul_f32 v[20:21], v[20:21], v[40:41] op_sel_hi:[1,0]
	v_mul_f32_e32 v42, v5, v40
	v_pk_mul_f32 v[10:11], v[20:21], v[10:11] op_sel:[1,0] op_sel_hi:[0,1]
	v_pk_mul_f32 v[28:29], v[20:21], v[28:29] op_sel:[1,0] op_sel_hi:[0,1]
	v_pk_mul_f32 v[12:13], v[20:21], v[12:13] op_sel:[1,0] op_sel_hi:[0,1]
	v_pk_mul_f32 v[36:37], v[20:21], v[36:37] op_sel:[1,0] op_sel_hi:[0,1]
	v_pk_fma_f32 v[10:11], v[20:21], v[24:25], v[10:11]
	v_pk_fma_f32 v[24:25], v[20:21], v[26:27], v[28:29]
	v_pk_fma_f32 v[12:13], v[20:21], v[30:31], v[12:13]
	v_pk_fma_f32 v[20:21], v[20:21], v[34:35], v[36:37]
	v_pk_fma_f32 v[10:11], v[42:43], v[38:39], v[10:11] op_sel_hi:[0,1,1]
	v_pk_fma_f32 v[14:15], v[42:43], v[14:15], v[24:25] op_sel_hi:[0,1,1]
	v_pk_fma_f32 v[12:13], v[42:43], v[18:19], v[12:13] op_sel_hi:[0,1,1]
	v_pk_fma_f32 v[16:17], v[42:43], v[16:17], v[20:21] op_sel_hi:[0,1,1]
	v_cvt_pk_bf16_f32 v10, v10, v11
	v_cvt_pk_bf16_f32 v11, v14, v15
	v_cvt_pk_bf16_f32 v12, v12, v13
	v_cvt_pk_bf16_f32 v13, v16, v17
	v_add_u32_e32 v8, 0x20000, v7
	global_store_dwordx4 v8, v[10:13], s[8:9] offset:1024
	s_waitcnt vmcnt(27)
	v_max3_f32 v5, v108, v109, v110
	v_sub_f32_e32 v9, v108, v5
	v_sub_f32_e32 v40, v109, v5
	v_and_b32_e32 v27, 0xffff0000, v97
	v_lshlrev_b32_e32 v28, 16, v97
	v_sub_f32_e32 v5, v110, v5
	v_lshlrev_b32_e32 v24, 16, v100
	v_and_b32_e32 v11, 0xffff0000, v100
	v_lshlrev_b32_e32 v38, 16, v104
	v_and_b32_e32 v39, 0xffff0000, v104
	v_lshlrev_b32_e32 v26, 16, v101
	v_and_b32_e32 v29, 0xffff0000, v101
	v_lshlrev_b32_e32 v14, 16, v105
	v_and_b32_e32 v15, 0xffff0000, v105
	v_lshlrev_b32_e32 v18, 16, v106
	v_and_b32_e32 v19, 0xffff0000, v106
	v_mul_f32_e32 v9, 0x3fb8aa3b, v9
	v_mul_f32_e32 v20, 0x3fb8aa3b, v40
	v_and_b32_e32 v35, 0xffff0000, v99
	v_lshlrev_b32_e32 v36, 16, v99
	v_lshlrev_b32_e32 v30, 16, v102
	v_and_b32_e32 v13, 0xffff0000, v102
	v_lshlrev_b32_e32 v34, 16, v103
	v_and_b32_e32 v37, 0xffff0000, v103
	v_lshlrev_b32_e32 v16, 16, v107
	v_and_b32_e32 v17, 0xffff0000, v107
	v_mul_f32_e32 v5, 0x3fb8aa3b, v5
	v_exp_f32_e32 v21, v9
	v_exp_f32_e32 v20, v20
	v_exp_f32_e32 v5, v5
	v_and_b32_e32 v25, 0xffff0000, v96
	v_lshlrev_b32_e32 v10, 16, v96
	v_add_f32_e32 v9, v21, v20
	v_add_f32_e32 v9, v5, v9
	v_and_b32_e32 v31, 0xffff0000, v98
	v_rcp_f32_e32 v40, v9
	s_nop 0
	v_lshlrev_b32_e32 v12, 16, v98
	v_pk_mul_f32 v[20:21], v[20:21], v[40:41] op_sel_hi:[1,0]
	v_mul_f32_e32 v42, v5, v40
	v_pk_mul_f32 v[10:11], v[20:21], v[10:11] op_sel:[1,0] op_sel_hi:[0,1]
	v_pk_mul_f32 v[28:29], v[20:21], v[28:29] op_sel:[1,0] op_sel_hi:[0,1]
	v_pk_mul_f32 v[12:13], v[20:21], v[12:13] op_sel:[1,0] op_sel_hi:[0,1]
	v_pk_mul_f32 v[36:37], v[20:21], v[36:37] op_sel:[1,0] op_sel_hi:[0,1]
	v_pk_fma_f32 v[10:11], v[20:21], v[24:25], v[10:11]
	v_pk_fma_f32 v[24:25], v[20:21], v[26:27], v[28:29]
	v_pk_fma_f32 v[12:13], v[20:21], v[30:31], v[12:13]
	v_pk_fma_f32 v[20:21], v[20:21], v[34:35], v[36:37]
	v_pk_fma_f32 v[10:11], v[42:43], v[38:39], v[10:11] op_sel_hi:[0,1,1]
	v_pk_fma_f32 v[14:15], v[42:43], v[14:15], v[24:25] op_sel_hi:[0,1,1]
	v_pk_fma_f32 v[12:13], v[42:43], v[18:19], v[12:13] op_sel_hi:[0,1,1]
	v_pk_fma_f32 v[16:17], v[42:43], v[16:17], v[20:21] op_sel_hi:[0,1,1]
	v_cvt_pk_bf16_f32 v10, v10, v11
	v_cvt_pk_bf16_f32 v11, v14, v15
	v_cvt_pk_bf16_f32 v12, v12, v13
	v_cvt_pk_bf16_f32 v13, v16, v17
	v_add_u32_e32 v8, 0x30000, v7
	global_store_dwordx4 v8, v[10:13], s[8:9] offset:1024
	s_waitcnt vmcnt(22)
	v_max3_f32 v5, v140, v141, v142
	v_sub_f32_e32 v9, v140, v5
	v_sub_f32_e32 v40, v141, v5
	v_and_b32_e32 v27, 0xffff0000, v129
	v_lshlrev_b32_e32 v28, 16, v129
	v_sub_f32_e32 v5, v142, v5
	v_lshlrev_b32_e32 v24, 16, v132
	v_and_b32_e32 v11, 0xffff0000, v132
	v_lshlrev_b32_e32 v38, 16, v136
	v_and_b32_e32 v39, 0xffff0000, v136
	v_lshlrev_b32_e32 v26, 16, v133
	v_and_b32_e32 v29, 0xffff0000, v133
	v_lshlrev_b32_e32 v14, 16, v137
	v_and_b32_e32 v15, 0xffff0000, v137
	v_lshlrev_b32_e32 v18, 16, v138
	v_and_b32_e32 v19, 0xffff0000, v138
	v_mul_f32_e32 v9, 0x3fb8aa3b, v9
	v_mul_f32_e32 v20, 0x3fb8aa3b, v40
	v_and_b32_e32 v35, 0xffff0000, v131
	v_lshlrev_b32_e32 v36, 16, v131
	v_lshlrev_b32_e32 v30, 16, v134
	v_and_b32_e32 v13, 0xffff0000, v134
	v_lshlrev_b32_e32 v34, 16, v135
	v_and_b32_e32 v37, 0xffff0000, v135
	v_lshlrev_b32_e32 v16, 16, v139
	v_and_b32_e32 v17, 0xffff0000, v139
	v_mul_f32_e32 v5, 0x3fb8aa3b, v5
	v_exp_f32_e32 v21, v9
	v_exp_f32_e32 v20, v20
	v_exp_f32_e32 v5, v5
	v_and_b32_e32 v25, 0xffff0000, v128
	v_lshlrev_b32_e32 v10, 16, v128
	v_add_f32_e32 v9, v21, v20
	v_add_f32_e32 v9, v5, v9
	v_and_b32_e32 v31, 0xffff0000, v130
	v_rcp_f32_e32 v40, v9
	s_nop 0
	v_lshlrev_b32_e32 v12, 16, v130
	v_pk_mul_f32 v[20:21], v[20:21], v[40:41] op_sel_hi:[1,0]
	v_mul_f32_e32 v42, v5, v40
	v_pk_mul_f32 v[10:11], v[20:21], v[10:11] op_sel:[1,0] op_sel_hi:[0,1]
	v_pk_mul_f32 v[28:29], v[20:21], v[28:29] op_sel:[1,0] op_sel_hi:[0,1]
	v_pk_mul_f32 v[12:13], v[20:21], v[12:13] op_sel:[1,0] op_sel_hi:[0,1]
	v_pk_mul_f32 v[36:37], v[20:21], v[36:37] op_sel:[1,0] op_sel_hi:[0,1]
	v_pk_fma_f32 v[10:11], v[20:21], v[24:25], v[10:11]
	v_pk_fma_f32 v[24:25], v[20:21], v[26:27], v[28:29]
	v_pk_fma_f32 v[12:13], v[20:21], v[30:31], v[12:13]
	v_pk_fma_f32 v[20:21], v[20:21], v[34:35], v[36:37]
	v_pk_fma_f32 v[10:11], v[42:43], v[38:39], v[10:11] op_sel_hi:[0,1,1]
	v_pk_fma_f32 v[14:15], v[42:43], v[14:15], v[24:25] op_sel_hi:[0,1,1]
	v_pk_fma_f32 v[12:13], v[42:43], v[18:19], v[12:13] op_sel_hi:[0,1,1]
	v_pk_fma_f32 v[16:17], v[42:43], v[16:17], v[20:21] op_sel_hi:[0,1,1]
	v_cvt_pk_bf16_f32 v10, v10, v11
	v_cvt_pk_bf16_f32 v11, v14, v15
	v_cvt_pk_bf16_f32 v12, v12, v13
	v_cvt_pk_bf16_f32 v13, v16, v17
	v_add_u32_e32 v8, 0x40000, v7
	global_store_dwordx4 v8, v[10:13], s[8:9] offset:1024
	s_waitcnt vmcnt(17)
	v_max3_f32 v5, v164, v165, v166
	v_sub_f32_e32 v9, v164, v5
	v_sub_f32_e32 v40, v165, v5
	v_and_b32_e32 v27, 0xffff0000, v153
	v_lshlrev_b32_e32 v28, 16, v153
	v_sub_f32_e32 v5, v166, v5
	v_lshlrev_b32_e32 v24, 16, v156
	v_and_b32_e32 v11, 0xffff0000, v156
	v_lshlrev_b32_e32 v38, 16, v160
	v_and_b32_e32 v39, 0xffff0000, v160
	v_lshlrev_b32_e32 v26, 16, v157
	v_and_b32_e32 v29, 0xffff0000, v157
	v_lshlrev_b32_e32 v14, 16, v161
	v_and_b32_e32 v15, 0xffff0000, v161
	v_lshlrev_b32_e32 v18, 16, v162
	v_and_b32_e32 v19, 0xffff0000, v162
	v_mul_f32_e32 v9, 0x3fb8aa3b, v9
	v_mul_f32_e32 v20, 0x3fb8aa3b, v40
	v_and_b32_e32 v35, 0xffff0000, v155
	v_lshlrev_b32_e32 v36, 16, v155
	v_lshlrev_b32_e32 v30, 16, v158
	v_and_b32_e32 v13, 0xffff0000, v158
	v_lshlrev_b32_e32 v34, 16, v159
	v_and_b32_e32 v37, 0xffff0000, v159
	v_lshlrev_b32_e32 v16, 16, v163
	v_and_b32_e32 v17, 0xffff0000, v163
	v_mul_f32_e32 v5, 0x3fb8aa3b, v5
	v_exp_f32_e32 v21, v9
	v_exp_f32_e32 v20, v20
	v_exp_f32_e32 v5, v5
	v_and_b32_e32 v25, 0xffff0000, v152
	v_lshlrev_b32_e32 v10, 16, v152
	v_add_f32_e32 v9, v21, v20
	v_add_f32_e32 v9, v5, v9
	v_and_b32_e32 v31, 0xffff0000, v154
	v_rcp_f32_e32 v40, v9
	s_nop 0
	v_lshlrev_b32_e32 v12, 16, v154
	v_pk_mul_f32 v[20:21], v[20:21], v[40:41] op_sel_hi:[1,0]
	v_mul_f32_e32 v42, v5, v40
	v_pk_mul_f32 v[10:11], v[20:21], v[10:11] op_sel:[1,0] op_sel_hi:[0,1]
	v_pk_mul_f32 v[28:29], v[20:21], v[28:29] op_sel:[1,0] op_sel_hi:[0,1]
	v_pk_mul_f32 v[12:13], v[20:21], v[12:13] op_sel:[1,0] op_sel_hi:[0,1]
	v_pk_mul_f32 v[36:37], v[20:21], v[36:37] op_sel:[1,0] op_sel_hi:[0,1]
	v_pk_fma_f32 v[10:11], v[20:21], v[24:25], v[10:11]
	v_pk_fma_f32 v[24:25], v[20:21], v[26:27], v[28:29]
	v_pk_fma_f32 v[12:13], v[20:21], v[30:31], v[12:13]
	v_pk_fma_f32 v[20:21], v[20:21], v[34:35], v[36:37]
	v_pk_fma_f32 v[10:11], v[42:43], v[38:39], v[10:11] op_sel_hi:[0,1,1]
	v_pk_fma_f32 v[14:15], v[42:43], v[14:15], v[24:25] op_sel_hi:[0,1,1]
	v_pk_fma_f32 v[12:13], v[42:43], v[18:19], v[12:13] op_sel_hi:[0,1,1]
	v_pk_fma_f32 v[16:17], v[42:43], v[16:17], v[20:21] op_sel_hi:[0,1,1]
	v_cvt_pk_bf16_f32 v10, v10, v11
	v_cvt_pk_bf16_f32 v11, v14, v15
	v_cvt_pk_bf16_f32 v12, v12, v13
	v_cvt_pk_bf16_f32 v13, v16, v17
	v_add_u32_e32 v8, 0x50000, v7
	global_store_dwordx4 v8, v[10:13], s[8:9] offset:1024
	s_waitcnt vmcnt(12)
	v_max3_f32 v5, v218, v219, v220
	v_sub_f32_e32 v9, v218, v5
	v_sub_f32_e32 v40, v219, v5
	v_and_b32_e32 v27, 0xffff0000, v207
	v_lshlrev_b32_e32 v28, 16, v207
	v_sub_f32_e32 v5, v220, v5
	v_lshlrev_b32_e32 v24, 16, v210
	v_and_b32_e32 v11, 0xffff0000, v210
	v_lshlrev_b32_e32 v38, 16, v214
	v_and_b32_e32 v39, 0xffff0000, v214
	v_lshlrev_b32_e32 v26, 16, v211
	v_and_b32_e32 v29, 0xffff0000, v211
	v_lshlrev_b32_e32 v14, 16, v215
	v_and_b32_e32 v15, 0xffff0000, v215
	v_lshlrev_b32_e32 v18, 16, v216
	v_and_b32_e32 v19, 0xffff0000, v216
	v_mul_f32_e32 v9, 0x3fb8aa3b, v9
	v_mul_f32_e32 v20, 0x3fb8aa3b, v40
	v_and_b32_e32 v35, 0xffff0000, v209
	v_lshlrev_b32_e32 v36, 16, v209
	v_lshlrev_b32_e32 v30, 16, v212
	v_and_b32_e32 v13, 0xffff0000, v212
	v_lshlrev_b32_e32 v34, 16, v213
	v_and_b32_e32 v37, 0xffff0000, v213
	v_lshlrev_b32_e32 v16, 16, v217
	v_and_b32_e32 v17, 0xffff0000, v217
	v_mul_f32_e32 v5, 0x3fb8aa3b, v5
	v_exp_f32_e32 v21, v9
	v_exp_f32_e32 v20, v20
	v_exp_f32_e32 v5, v5
	v_and_b32_e32 v25, 0xffff0000, v206
	v_lshlrev_b32_e32 v10, 16, v206
	v_add_f32_e32 v9, v21, v20
	v_add_f32_e32 v9, v5, v9
	v_and_b32_e32 v31, 0xffff0000, v208
	v_rcp_f32_e32 v40, v9
	s_nop 0
	v_lshlrev_b32_e32 v12, 16, v208
	v_pk_mul_f32 v[20:21], v[20:21], v[40:41] op_sel_hi:[1,0]
	v_mul_f32_e32 v42, v5, v40
	v_pk_mul_f32 v[10:11], v[20:21], v[10:11] op_sel:[1,0] op_sel_hi:[0,1]
	v_pk_mul_f32 v[28:29], v[20:21], v[28:29] op_sel:[1,0] op_sel_hi:[0,1]
	v_pk_mul_f32 v[12:13], v[20:21], v[12:13] op_sel:[1,0] op_sel_hi:[0,1]
	v_pk_mul_f32 v[36:37], v[20:21], v[36:37] op_sel:[1,0] op_sel_hi:[0,1]
	v_pk_fma_f32 v[10:11], v[20:21], v[24:25], v[10:11]
	v_pk_fma_f32 v[24:25], v[20:21], v[26:27], v[28:29]
	v_pk_fma_f32 v[12:13], v[20:21], v[30:31], v[12:13]
	v_pk_fma_f32 v[20:21], v[20:21], v[34:35], v[36:37]
	v_pk_fma_f32 v[10:11], v[42:43], v[38:39], v[10:11] op_sel_hi:[0,1,1]
	v_pk_fma_f32 v[14:15], v[42:43], v[14:15], v[24:25] op_sel_hi:[0,1,1]
	v_pk_fma_f32 v[12:13], v[42:43], v[18:19], v[12:13] op_sel_hi:[0,1,1]
	v_pk_fma_f32 v[16:17], v[42:43], v[16:17], v[20:21] op_sel_hi:[0,1,1]
	v_cvt_pk_bf16_f32 v10, v10, v11
	v_cvt_pk_bf16_f32 v11, v14, v15
	v_cvt_pk_bf16_f32 v12, v12, v13
	v_cvt_pk_bf16_f32 v13, v16, v17
	v_add_u32_e32 v8, 0x60000, v7
	global_store_dwordx4 v8, v[10:13], s[8:9] offset:1024
	s_waitcnt vmcnt(7)
	v_max3_f32 v5, v244, v245, v246
	v_sub_f32_e32 v9, v244, v5
	v_sub_f32_e32 v40, v245, v5
	v_and_b32_e32 v27, 0xffff0000, v233
	v_lshlrev_b32_e32 v28, 16, v233
	v_sub_f32_e32 v5, v246, v5
	v_lshlrev_b32_e32 v24, 16, v236
	v_and_b32_e32 v11, 0xffff0000, v236
	v_lshlrev_b32_e32 v38, 16, v240
	v_and_b32_e32 v39, 0xffff0000, v240
	v_lshlrev_b32_e32 v26, 16, v237
	v_and_b32_e32 v29, 0xffff0000, v237
	v_lshlrev_b32_e32 v14, 16, v241
	v_and_b32_e32 v15, 0xffff0000, v241
	v_lshlrev_b32_e32 v18, 16, v242
	v_and_b32_e32 v19, 0xffff0000, v242
	v_mul_f32_e32 v9, 0x3fb8aa3b, v9
	v_mul_f32_e32 v20, 0x3fb8aa3b, v40
	v_and_b32_e32 v35, 0xffff0000, v235
	v_lshlrev_b32_e32 v36, 16, v235
	v_lshlrev_b32_e32 v30, 16, v238
	v_and_b32_e32 v13, 0xffff0000, v238
	v_lshlrev_b32_e32 v34, 16, v239
	v_and_b32_e32 v37, 0xffff0000, v239
	v_lshlrev_b32_e32 v16, 16, v243
	v_and_b32_e32 v17, 0xffff0000, v243
	v_mul_f32_e32 v5, 0x3fb8aa3b, v5
	v_exp_f32_e32 v21, v9
	v_exp_f32_e32 v20, v20
	v_exp_f32_e32 v5, v5
	v_and_b32_e32 v25, 0xffff0000, v232
	v_lshlrev_b32_e32 v10, 16, v232
	v_add_f32_e32 v9, v21, v20
	v_add_f32_e32 v9, v5, v9
	v_and_b32_e32 v31, 0xffff0000, v234
	v_rcp_f32_e32 v40, v9
	s_nop 0
	v_lshlrev_b32_e32 v12, 16, v234
	v_pk_mul_f32 v[20:21], v[20:21], v[40:41] op_sel_hi:[1,0]
	v_mul_f32_e32 v42, v5, v40
	v_pk_mul_f32 v[10:11], v[20:21], v[10:11] op_sel:[1,0] op_sel_hi:[0,1]
	v_pk_mul_f32 v[28:29], v[20:21], v[28:29] op_sel:[1,0] op_sel_hi:[0,1]
	v_pk_mul_f32 v[12:13], v[20:21], v[12:13] op_sel:[1,0] op_sel_hi:[0,1]
	v_pk_mul_f32 v[36:37], v[20:21], v[36:37] op_sel:[1,0] op_sel_hi:[0,1]
	v_pk_fma_f32 v[10:11], v[20:21], v[24:25], v[10:11]
	v_pk_fma_f32 v[24:25], v[20:21], v[26:27], v[28:29]
	v_pk_fma_f32 v[12:13], v[20:21], v[30:31], v[12:13]
	v_pk_fma_f32 v[20:21], v[20:21], v[34:35], v[36:37]
	v_pk_fma_f32 v[10:11], v[42:43], v[38:39], v[10:11] op_sel_hi:[0,1,1]
	v_pk_fma_f32 v[14:15], v[42:43], v[14:15], v[24:25] op_sel_hi:[0,1,1]
	v_pk_fma_f32 v[12:13], v[42:43], v[18:19], v[12:13] op_sel_hi:[0,1,1]
	v_pk_fma_f32 v[16:17], v[42:43], v[16:17], v[20:21] op_sel_hi:[0,1,1]
	v_cvt_pk_bf16_f32 v10, v10, v11
	v_cvt_pk_bf16_f32 v11, v14, v15
	v_cvt_pk_bf16_f32 v12, v12, v13
	v_cvt_pk_bf16_f32 v13, v16, v17
	v_add_u32_e32 v8, 0x70000, v7
	global_store_dwordx4 v8, v[10:13], s[8:9] offset:1024
	s_waitcnt vmcnt(0)
	s_barrier
	s_mov_b64 s[0:1], exec
	v_readlane_b32 s2, v254, 29
	v_readlane_b32 s3, v254, 30
	s_and_b64 s[2:3], s[0:1], s[2:3]
	s_mov_b64 exec, s[2:3]
	s_cbranch_execz .LBB0_605
	s_andn2_b64 vcc, exec, s[42:43]
	s_cbranch_vccnz .LBB0_594
	buffer_wbl2 sc1
	s_waitcnt vmcnt(0)
	s_waitcnt vmcnt(0)
